# speedup vs baseline: 1.0050x; 1.0050x over previous
.LBB0_138:
	ds_read_b128 v[140:143], v138
	ds_read_b128 v[144:147], v138 offset:1024
	ds_read_b128 v[148:151], v138 offset:2048
	ds_read_b128 v[152:155], v138 offset:3072
	s_add_u32 s8, s6, s65
	s_addc_u32 s9, s7, s66
	s_mov_b32 m0, s76
	s_add_u32 s98, s8, s44
	s_addc_u32 s99, s9, s45
	global_load_lds_dwordx4 v129, s[98:99]
	s_mov_b32 m0, s75
	s_nop 0
	global_load_lds_dwordx4 v130, s[98:99]
	ds_read_b128 v[156:159], v134
	ds_read_b128 v[160:163], v134 offset:1024
	ds_read_b128 v[164:167], v133
	ds_read_b128 v[168:171], v133 offset:1024
	ds_read_b128 v[172:175], v132
	ds_read_b128 v[176:179], v132 offset:1024
	ds_read_b128 v[180:183], v131
	ds_read_b128 v[184:187], v131 offset:1024
	s_waitcnt lgkmcnt(8)
	s_barrier
	s_waitcnt lgkmcnt(7)
	v_mfma_f32_16x16x32_bf16 v[124:127], v[140:143], v[156:159], v[124:127]
	v_mfma_f32_16x16x32_bf16 v[120:123], v[148:151], v[156:159], v[120:123]
	s_waitcnt lgkmcnt(5)
	v_mfma_f32_16x16x32_bf16 v[116:119], v[140:143], v[164:167], v[116:119]
	v_mfma_f32_16x16x32_bf16 v[112:115], v[148:151], v[164:167], v[112:115]
	s_waitcnt lgkmcnt(3)
	v_mfma_f32_16x16x32_bf16 v[108:111], v[140:143], v[172:175], v[108:111]
	v_mfma_f32_16x16x32_bf16 v[104:107], v[148:151], v[172:175], v[104:107]
	s_waitcnt lgkmcnt(1)
	v_mfma_f32_16x16x32_bf16 v[100:103], v[140:143], v[180:183], v[100:103]
	v_mfma_f32_16x16x32_bf16 v[96:99], v[148:151], v[180:183], v[96:99]
	v_mfma_f32_16x16x32_bf16 v[124:127], v[144:147], v[160:163], v[124:127]
	v_mfma_f32_16x16x32_bf16 v[120:123], v[152:155], v[160:163], v[120:123]
	v_mfma_f32_16x16x32_bf16 v[116:119], v[144:147], v[168:171], v[116:119]
	v_mfma_f32_16x16x32_bf16 v[112:115], v[152:155], v[168:171], v[112:115]
	v_mfma_f32_16x16x32_bf16 v[108:111], v[144:147], v[176:179], v[108:111]
	v_mfma_f32_16x16x32_bf16 v[104:107], v[152:155], v[176:179], v[104:107]
	s_waitcnt lgkmcnt(0)
	v_mfma_f32_16x16x32_bf16 v[100:103], v[144:147], v[184:187], v[100:103]
	v_mfma_f32_16x16x32_bf16 v[96:99], v[152:155], v[184:187], v[96:99]
	s_barrier
	s_add_u32 s10, s6, s36
	s_addc_u32 s11, s7, s37
	ds_read_b128 v[188:191], v137
	ds_read_b128 v[192:195], v137 offset:1024
	ds_read_b128 v[202:205], v137 offset:2048
	ds_read_b128 v[206:209], v137 offset:3072
	s_mov_b32 m0, s63
	s_add_u32 s98, s10, s46
	s_addc_u32 s99, s11, s47
	global_load_lds_dwordx4 v129, s[98:99]
	s_mov_b32 m0, s64
	s_nop 0
	global_load_lds_dwordx4 v130, s[98:99]
	s_barrier
	s_waitcnt lgkmcnt(3)
	v_mfma_f32_16x16x32_bf16 v[92:95], v[188:191], v[156:159], v[92:95]
	s_waitcnt lgkmcnt(1)
	v_mfma_f32_16x16x32_bf16 v[88:91], v[202:205], v[156:159], v[88:91]
	v_mfma_f32_16x16x32_bf16 v[84:87], v[188:191], v[164:167], v[84:87]
	v_mfma_f32_16x16x32_bf16 v[80:83], v[202:205], v[164:167], v[80:83]
	v_mfma_f32_16x16x32_bf16 v[76:79], v[188:191], v[172:175], v[76:79]
	v_mfma_f32_16x16x32_bf16 v[72:75], v[202:205], v[172:175], v[72:75]
	v_mfma_f32_16x16x32_bf16 v[68:71], v[188:191], v[180:183], v[68:71]
	v_mfma_f32_16x16x32_bf16 v[64:67], v[202:205], v[180:183], v[64:67]
	v_mfma_f32_16x16x32_bf16 v[92:95], v[192:195], v[160:163], v[92:95]
	s_waitcnt lgkmcnt(0)
	v_mfma_f32_16x16x32_bf16 v[88:91], v[206:209], v[160:163], v[88:91]
	v_mfma_f32_16x16x32_bf16 v[84:87], v[192:195], v[168:171], v[84:87]
	v_mfma_f32_16x16x32_bf16 v[80:83], v[206:209], v[168:171], v[80:83]
	v_mfma_f32_16x16x32_bf16 v[76:79], v[192:195], v[176:179], v[76:79]
	v_mfma_f32_16x16x32_bf16 v[72:75], v[206:209], v[176:179], v[72:75]
	v_mfma_f32_16x16x32_bf16 v[68:71], v[192:195], v[184:187], v[68:71]
	v_mfma_f32_16x16x32_bf16 v[64:67], v[206:209], v[184:187], v[64:67]
	s_barrier
	ds_read_b128 v[156:159], v134 offset:16384
	ds_read_b128 v[160:163], v134 offset:17408
	ds_read_b128 v[164:167], v133 offset:16384
	ds_read_b128 v[168:171], v133 offset:17408
	ds_read_b128 v[172:175], v132 offset:16384
	ds_read_b128 v[176:179], v132 offset:17408
	ds_read_b128 v[180:183], v131 offset:16384
	ds_read_b128 v[184:187], v131 offset:17408
	s_mov_b32 m0, s62
	s_add_u32 s98, s8, s48
	s_addc_u32 s99, s9, s49
	global_load_lds_dwordx4 v129, s[98:99]
	s_mov_b32 m0, s67
	s_nop 0
	global_load_lds_dwordx4 v130, s[98:99]
	s_barrier
	s_waitcnt lgkmcnt(7)
	v_mfma_f32_16x16x32_bf16 v[60:63], v[140:143], v[156:159], v[60:63]
	v_mfma_f32_16x16x32_bf16 v[56:59], v[148:151], v[156:159], v[56:59]
	s_waitcnt lgkmcnt(5)
	v_mfma_f32_16x16x32_bf16 v[52:55], v[140:143], v[164:167], v[52:55]
	v_mfma_f32_16x16x32_bf16 v[48:51], v[148:151], v[164:167], v[48:51]
	s_waitcnt lgkmcnt(3)
	v_mfma_f32_16x16x32_bf16 v[44:47], v[140:143], v[172:175], v[44:47]
	v_mfma_f32_16x16x32_bf16 v[40:43], v[148:151], v[172:175], v[40:43]
	s_waitcnt lgkmcnt(1)
	v_mfma_f32_16x16x32_bf16 v[36:39], v[140:143], v[180:183], v[36:39]
	v_mfma_f32_16x16x32_bf16 v[32:35], v[148:151], v[180:183], v[32:35]
	v_mfma_f32_16x16x32_bf16 v[60:63], v[144:147], v[160:163], v[60:63]
	v_mfma_f32_16x16x32_bf16 v[56:59], v[152:155], v[160:163], v[56:59]
	v_mfma_f32_16x16x32_bf16 v[52:55], v[144:147], v[168:171], v[52:55]
	v_mfma_f32_16x16x32_bf16 v[48:51], v[152:155], v[168:171], v[48:51]
	v_mfma_f32_16x16x32_bf16 v[44:47], v[144:147], v[176:179], v[44:47]
	v_mfma_f32_16x16x32_bf16 v[40:43], v[152:155], v[176:179], v[40:43]
	s_waitcnt lgkmcnt(0)
	v_mfma_f32_16x16x32_bf16 v[36:39], v[144:147], v[184:187], v[36:39]
	v_mfma_f32_16x16x32_bf16 v[32:35], v[152:155], v[184:187], v[32:35]
	s_barrier
	s_mov_b32 m0, s68
	s_add_u32 s98, s10, s50
	s_addc_u32 s99, s11, s51
	global_load_lds_dwordx4 v129, s[98:99]
	s_mov_b32 m0, s69
	s_nop 0
	global_load_lds_dwordx4 v130, s[98:99]
	s_waitcnt vmcnt(6)
	s_barrier
	v_mfma_f32_16x16x32_bf16 v[28:31], v[188:191], v[156:159], v[28:31]
	v_mfma_f32_16x16x32_bf16 v[24:27], v[202:205], v[156:159], v[24:27]
	v_mfma_f32_16x16x32_bf16 v[20:23], v[188:191], v[164:167], v[20:23]
	v_mfma_f32_16x16x32_bf16 v[16:19], v[202:205], v[164:167], v[16:19]
	v_mfma_f32_16x16x32_bf16 v[12:15], v[188:191], v[172:175], v[12:15]
	v_mfma_f32_16x16x32_bf16 v[8:11], v[202:205], v[172:175], v[8:11]
	v_mfma_f32_16x16x32_bf16 v[4:7], v[188:191], v[180:183], v[4:7]
	v_mfma_f32_16x16x32_bf16 v[0:3], v[202:205], v[180:183], v[0:3]
	v_mfma_f32_16x16x32_bf16 v[28:31], v[192:195], v[160:163], v[28:31]
	v_mfma_f32_16x16x32_bf16 v[24:27], v[206:209], v[160:163], v[24:27]
	v_mfma_f32_16x16x32_bf16 v[20:23], v[192:195], v[168:171], v[20:23]
	v_mfma_f32_16x16x32_bf16 v[16:19], v[206:209], v[168:171], v[16:19]
	v_mfma_f32_16x16x32_bf16 v[12:15], v[192:195], v[176:179], v[12:15]
	v_mfma_f32_16x16x32_bf16 v[8:11], v[206:209], v[176:179], v[8:11]
	v_mfma_f32_16x16x32_bf16 v[4:7], v[192:195], v[184:187], v[4:7]
	v_mfma_f32_16x16x32_bf16 v[0:3], v[206:209], v[184:187], v[0:3]
	s_barrier
	ds_read_b128 v[140:143], v136
	ds_read_b128 v[144:147], v136 offset:1024
	ds_read_b128 v[148:151], v136 offset:2048
	ds_read_b128 v[152:155], v136 offset:3072
	s_mov_b32 m0, s70
	s_add_u32 s98, s8, s90
	s_addc_u32 s99, s9, s91
	global_load_lds_dwordx4 v129, s[98:99]
	s_mov_b32 m0, s71
	s_nop 0
	global_load_lds_dwordx4 v130, s[98:99]
	ds_read_b128 v[156:159], v134 offset:32768
	ds_read_b128 v[160:163], v134 offset:33792
	ds_read_b128 v[164:167], v133 offset:32768
	ds_read_b128 v[168:171], v133 offset:33792
	ds_read_b128 v[172:175], v132 offset:32768
	ds_read_b128 v[176:179], v132 offset:33792
	ds_read_b128 v[180:183], v131 offset:32768
	ds_read_b128 v[184:187], v131 offset:33792
	s_waitcnt lgkmcnt(8)
	s_barrier
	s_waitcnt lgkmcnt(7)
	v_mfma_f32_16x16x32_bf16 v[124:127], v[140:143], v[156:159], v[124:127]
	v_mfma_f32_16x16x32_bf16 v[120:123], v[148:151], v[156:159], v[120:123]
	s_waitcnt lgkmcnt(5)
	v_mfma_f32_16x16x32_bf16 v[116:119], v[140:143], v[164:167], v[116:119]
	v_mfma_f32_16x16x32_bf16 v[112:115], v[148:151], v[164:167], v[112:115]
	s_waitcnt lgkmcnt(3)
	v_mfma_f32_16x16x32_bf16 v[108:111], v[140:143], v[172:175], v[108:111]
	v_mfma_f32_16x16x32_bf16 v[104:107], v[148:151], v[172:175], v[104:107]
	s_waitcnt lgkmcnt(1)
	v_mfma_f32_16x16x32_bf16 v[100:103], v[140:143], v[180:183], v[100:103]
	v_mfma_f32_16x16x32_bf16 v[96:99], v[148:151], v[180:183], v[96:99]
	v_mfma_f32_16x16x32_bf16 v[124:127], v[144:147], v[160:163], v[124:127]
	v_mfma_f32_16x16x32_bf16 v[120:123], v[152:155], v[160:163], v[120:123]
	v_mfma_f32_16x16x32_bf16 v[116:119], v[144:147], v[168:171], v[116:119]
	v_mfma_f32_16x16x32_bf16 v[112:115], v[152:155], v[168:171], v[112:115]
	v_mfma_f32_16x16x32_bf16 v[108:111], v[144:147], v[176:179], v[108:111]
	v_mfma_f32_16x16x32_bf16 v[104:107], v[152:155], v[176:179], v[104:107]
	s_waitcnt lgkmcnt(0)
	v_mfma_f32_16x16x32_bf16 v[100:103], v[144:147], v[184:187], v[100:103]
	v_mfma_f32_16x16x32_bf16 v[96:99], v[152:155], v[184:187], v[96:99]
	s_barrier
	ds_read_b128 v[188:191], v135
	ds_read_b128 v[192:195], v135 offset:1024
	ds_read_b128 v[202:205], v135 offset:2048
	ds_read_b128 v[206:209], v135 offset:3072
	s_mov_b32 m0, s28
	s_add_u32 s98, s10, s92
	s_addc_u32 s99, s11, s93
	global_load_lds_dwordx4 v129, s[98:99]
	s_mov_b32 m0, s29
	s_nop 0
	global_load_lds_dwordx4 v130, s[98:99]
	s_barrier
	s_waitcnt lgkmcnt(3)
	v_mfma_f32_16x16x32_bf16 v[92:95], v[188:191], v[156:159], v[92:95]
	s_waitcnt lgkmcnt(1)
	v_mfma_f32_16x16x32_bf16 v[88:91], v[202:205], v[156:159], v[88:91]
	v_mfma_f32_16x16x32_bf16 v[84:87], v[188:191], v[164:167], v[84:87]
	v_mfma_f32_16x16x32_bf16 v[80:83], v[202:205], v[164:167], v[80:83]
	v_mfma_f32_16x16x32_bf16 v[76:79], v[188:191], v[172:175], v[76:79]
	v_mfma_f32_16x16x32_bf16 v[72:75], v[202:205], v[172:175], v[72:75]
	v_mfma_f32_16x16x32_bf16 v[68:71], v[188:191], v[180:183], v[68:71]
	v_mfma_f32_16x16x32_bf16 v[64:67], v[202:205], v[180:183], v[64:67]
	v_mfma_f32_16x16x32_bf16 v[92:95], v[192:195], v[160:163], v[92:95]
	s_waitcnt lgkmcnt(0)
	v_mfma_f32_16x16x32_bf16 v[88:91], v[206:209], v[160:163], v[88:91]
	v_mfma_f32_16x16x32_bf16 v[84:87], v[192:195], v[168:171], v[84:87]
	v_mfma_f32_16x16x32_bf16 v[80:83], v[206:209], v[168:171], v[80:83]
	v_mfma_f32_16x16x32_bf16 v[76:79], v[192:195], v[176:179], v[76:79]
	v_mfma_f32_16x16x32_bf16 v[72:75], v[206:209], v[176:179], v[72:75]
	v_mfma_f32_16x16x32_bf16 v[68:71], v[192:195], v[184:187], v[68:71]
	v_mfma_f32_16x16x32_bf16 v[64:67], v[206:209], v[184:187], v[64:67]
	v_mov_b32_e32 v210, v130
	s_barrier
	ds_read_b128 v[156:159], v134 offset:49152
	ds_read_b128 v[160:163], v134 offset:50176
	ds_read_b128 v[164:167], v133 offset:49152
	ds_read_b128 v[168:171], v133 offset:50176
	ds_read_b128 v[172:175], v132 offset:49152
	ds_read_b128 v[176:179], v132 offset:50176
	ds_read_b128 v[180:183], v131 offset:49152
	ds_read_b128 v[184:187], v131 offset:50176
	v_mov_b32_e32 v211, v197
	s_mov_b32 m0, s72
	s_add_u32 s98, s8, s96
	s_addc_u32 s99, s9, s97
	global_load_lds_dwordx4 v129, s[98:99]
	s_mov_b32 m0, s73
	s_nop 0
	global_load_lds_dwordx4 v130, s[98:99]
	s_barrier
	s_waitcnt lgkmcnt(7)
	v_mfma_f32_16x16x32_bf16 v[60:63], v[140:143], v[156:159], v[60:63]
	v_mfma_f32_16x16x32_bf16 v[56:59], v[148:151], v[156:159], v[56:59]
	s_waitcnt lgkmcnt(5)
	v_mfma_f32_16x16x32_bf16 v[52:55], v[140:143], v[164:167], v[52:55]
	v_mfma_f32_16x16x32_bf16 v[48:51], v[148:151], v[164:167], v[48:51]
	s_waitcnt lgkmcnt(3)
	v_mfma_f32_16x16x32_bf16 v[44:47], v[140:143], v[172:175], v[44:47]
	v_mfma_f32_16x16x32_bf16 v[40:43], v[148:151], v[172:175], v[40:43]
	s_waitcnt lgkmcnt(1)
	v_mfma_f32_16x16x32_bf16 v[36:39], v[140:143], v[180:183], v[36:39]
	v_mfma_f32_16x16x32_bf16 v[32:35], v[148:151], v[180:183], v[32:35]
	v_mfma_f32_16x16x32_bf16 v[60:63], v[144:147], v[160:163], v[60:63]
	v_mfma_f32_16x16x32_bf16 v[56:59], v[152:155], v[160:163], v[56:59]
	v_mfma_f32_16x16x32_bf16 v[52:55], v[144:147], v[168:171], v[52:55]
	v_mfma_f32_16x16x32_bf16 v[48:51], v[152:155], v[168:171], v[48:51]
	v_mfma_f32_16x16x32_bf16 v[44:47], v[144:147], v[176:179], v[44:47]
	v_mfma_f32_16x16x32_bf16 v[40:43], v[152:155], v[176:179], v[40:43]
	s_waitcnt lgkmcnt(0)
	v_mfma_f32_16x16x32_bf16 v[36:39], v[144:147], v[184:187], v[36:39]
	v_mfma_f32_16x16x32_bf16 v[32:35], v[152:155], v[184:187], v[32:35]
	s_barrier
	v_mov_b32_e32 v196, v129
	s_mov_b32 m0, s33
	s_add_u32 s98, s10, vcc_lo
	s_addc_u32 s99, s11, vcc_hi
	global_load_lds_dwordx4 v129, s[98:99]
	s_mov_b32 m0, s74
	s_nop 0
	global_load_lds_dwordx4 v130, s[98:99]
	s_waitcnt vmcnt(6)
	s_barrier
	v_mfma_f32_16x16x32_bf16 v[28:31], v[188:191], v[156:159], v[28:31]
	v_mfma_f32_16x16x32_bf16 v[24:27], v[202:205], v[156:159], v[24:27]
	v_mfma_f32_16x16x32_bf16 v[20:23], v[188:191], v[164:167], v[20:23]
	v_mfma_f32_16x16x32_bf16 v[16:19], v[202:205], v[164:167], v[16:19]
	v_mfma_f32_16x16x32_bf16 v[12:15], v[188:191], v[172:175], v[12:15]
	v_mfma_f32_16x16x32_bf16 v[8:11], v[202:205], v[172:175], v[8:11]
	v_mfma_f32_16x16x32_bf16 v[4:7], v[188:191], v[180:183], v[4:7]
	v_mfma_f32_16x16x32_bf16 v[0:3], v[202:205], v[180:183], v[0:3]
	v_mfma_f32_16x16x32_bf16 v[28:31], v[192:195], v[160:163], v[28:31]
	v_mfma_f32_16x16x32_bf16 v[24:27], v[206:209], v[160:163], v[24:27]
	v_mfma_f32_16x16x32_bf16 v[20:23], v[192:195], v[168:171], v[20:23]
	v_mfma_f32_16x16x32_bf16 v[16:19], v[206:209], v[168:171], v[16:19]
	v_mfma_f32_16x16x32_bf16 v[12:15], v[192:195], v[176:179], v[12:15]
	v_mfma_f32_16x16x32_bf16 v[8:11], v[206:209], v[176:179], v[8:11]
	v_mfma_f32_16x16x32_bf16 v[4:7], v[192:195], v[184:187], v[4:7]
	v_mfma_f32_16x16x32_bf16 v[0:3], v[206:209], v[184:187], v[0:3]
	s_add_i32 s38, s38, 2
	s_add_u32 s6, s6, 0x100
	s_addc_u32 s7, s7, 0
	s_cmpk_lt_u32 s38, 0x54
	s_barrier
	s_cbranch_scc1 .LBB0_138
	s_add_u32 s4, s4, 0x2b80
	s_addc_u32 s5, s5, 0
	s_mov_b32 m0, s76
	ds_read_b128 v[140:143], v138
	ds_read_b128 v[144:147], v138 offset:1024
	ds_read_b128 v[148:151], v138 offset:2048
	ds_read_b128 v[152:155], v138 offset:3072
	ds_read_b128 v[156:159], v134
	ds_read_b128 v[160:163], v134 offset:1024
	ds_read_b128 v[164:167], v133
	ds_read_b128 v[168:171], v133 offset:1024
	ds_read_b128 v[172:175], v132
	ds_read_b128 v[176:179], v132 offset:1024
	ds_read_b128 v[180:183], v131
	ds_read_b128 v[184:187], v131 offset:1024
	s_nop 0
	global_load_lds_dwordx4 v129, s[4:5]
	s_mov_b32 m0, s75
	s_nop 0
	global_load_lds_dwordx4 v130, s[4:5]
	s_barrier
	s_waitcnt lgkmcnt(0)
	s_setprio 1
	s_waitcnt lgkmcnt(0)
	v_mfma_f32_16x16x32_bf16 v[124:127], v[140:143], v[156:159], v[124:127]
	v_mfma_f32_16x16x32_bf16 v[120:123], v[148:151], v[156:159], v[120:123]
	v_mfma_f32_16x16x32_bf16 v[116:119], v[140:143], v[164:167], v[116:119]
	v_mfma_f32_16x16x32_bf16 v[112:115], v[148:151], v[164:167], v[112:115]
	v_mfma_f32_16x16x32_bf16 v[108:111], v[140:143], v[172:175], v[108:111]
	v_mfma_f32_16x16x32_bf16 v[100:103], v[140:143], v[180:183], v[100:103]
	v_mfma_f32_16x16x32_bf16 v[96:99], v[148:151], v[180:183], v[96:99]
	v_mfma_f32_16x16x32_bf16 v[124:127], v[144:147], v[160:163], v[124:127]
	v_mfma_f32_16x16x32_bf16 v[120:123], v[152:155], v[160:163], v[120:123]
	v_mfma_f32_16x16x32_bf16 v[116:119], v[144:147], v[168:171], v[116:119]
	v_mfma_f32_16x16x32_bf16 v[112:115], v[152:155], v[168:171], v[112:115]
	v_mfma_f32_16x16x32_bf16 v[108:111], v[144:147], v[176:179], v[108:111]
	v_mfma_f32_16x16x32_bf16 v[104:107], v[148:151], v[172:175], v[104:107]
	v_mfma_f32_16x16x32_bf16 v[100:103], v[144:147], v[184:187], v[100:103]
	v_mfma_f32_16x16x32_bf16 v[96:99], v[152:155], v[184:187], v[96:99]
	v_mfma_f32_16x16x32_bf16 v[188:191], v[152:155], v[176:179], v[104:107]
	s_setprio 0
	s_barrier
	s_nop 2
	ds_read_b128 v[104:107], v137
	ds_read_b128 v[192:195], v137 offset:1024
	ds_read_b128 v[202:205], v137 offset:2048
	ds_read_b128 v[206:209], v137 offset:3072
	s_barrier
	s_waitcnt lgkmcnt(0)
	s_setprio 1
	s_waitcnt lgkmcnt(0)
	v_mfma_f32_16x16x32_bf16 v[92:95], v[104:107], v[156:159], v[92:95]
	v_mfma_f32_16x16x32_bf16 v[88:91], v[202:205], v[156:159], v[88:91]
	v_mfma_f32_16x16x32_bf16 v[80:83], v[202:205], v[164:167], v[80:83]
	v_mfma_f32_16x16x32_bf16 v[72:75], v[202:205], v[172:175], v[72:75]
	v_mfma_f32_16x16x32_bf16 v[64:67], v[202:205], v[180:183], v[64:67]
	v_mfma_f32_16x16x32_bf16 v[92:95], v[192:195], v[160:163], v[92:95]
	v_mfma_f32_16x16x32_bf16 v[88:91], v[206:209], v[160:163], v[88:91]
	v_mfma_f32_16x16x32_bf16 v[84:87], v[104:107], v[164:167], v[84:87]
	v_mfma_f32_16x16x32_bf16 v[80:83], v[206:209], v[168:171], v[80:83]
	v_mfma_f32_16x16x32_bf16 v[76:79], v[104:107], v[172:175], v[76:79]
	v_mfma_f32_16x16x32_bf16 v[72:75], v[206:209], v[176:179], v[72:75]
	v_mfma_f32_16x16x32_bf16 v[68:71], v[104:107], v[180:183], v[68:71]
	v_mfma_f32_16x16x32_bf16 v[64:67], v[206:209], v[184:187], v[64:67]
	v_mfma_f32_16x16x32_bf16 v[156:159], v[192:195], v[168:171], v[84:87]
	v_mfma_f32_16x16x32_bf16 v[160:163], v[192:195], v[176:179], v[76:79]
	v_mfma_f32_16x16x32_bf16 v[164:167], v[192:195], v[184:187], v[68:71]
	s_setprio 0
	s_barrier
	s_nop 1
	ds_read_b128 v[68:71], v134 offset:16384
	ds_read_b128 v[76:79], v134 offset:17408
	ds_read_b128 v[84:87], v133 offset:16384
	ds_read_b128 v[168:171], v133 offset:17408
	ds_read_b128 v[172:175], v132 offset:16384
	ds_read_b128 v[176:179], v132 offset:17408
	ds_read_b128 v[180:183], v131 offset:16384
	ds_read_b128 v[184:187], v131 offset:17408
	s_waitcnt vmcnt(4)
	s_barrier
	s_waitcnt lgkmcnt(0)
	s_setprio 1
	s_waitcnt lgkmcnt(0)
	v_mfma_f32_16x16x32_bf16 v[60:63], v[140:143], v[68:71], v[60:63]
	v_mfma_f32_16x16x32_bf16 v[56:59], v[148:151], v[68:71], v[56:59]
	v_mfma_f32_16x16x32_bf16 v[48:51], v[148:151], v[84:87], v[48:51]
	v_mfma_f32_16x16x32_bf16 v[32:35], v[148:151], v[180:183], v[32:35]
	v_mfma_f32_16x16x32_bf16 v[60:63], v[144:147], v[76:79], v[60:63]
	v_mfma_f32_16x16x32_bf16 v[56:59], v[152:155], v[76:79], v[56:59]
	v_mfma_f32_16x16x32_bf16 v[52:55], v[140:143], v[84:87], v[52:55]
	v_mfma_f32_16x16x32_bf16 v[48:51], v[152:155], v[168:171], v[48:51]
	v_mfma_f32_16x16x32_bf16 v[44:47], v[140:143], v[172:175], v[44:47]
	v_mfma_f32_16x16x32_bf16 v[40:43], v[148:151], v[172:175], v[40:43]
	v_mfma_f32_16x16x32_bf16 v[36:39], v[140:143], v[180:183], v[36:39]
	v_mfma_f32_16x16x32_bf16 v[32:35], v[152:155], v[184:187], v[32:35]
	v_mfma_f32_16x16x32_bf16 v[210:213], v[144:147], v[168:171], v[52:55]
	v_mfma_f32_16x16x32_bf16 v[214:217], v[144:147], v[176:179], v[44:47]
	v_mfma_f32_16x16x32_bf16 v[218:221], v[152:155], v[176:179], v[40:43]
	v_mfma_f32_16x16x32_bf16 v[138:141], v[144:147], v[184:187], v[36:39]
	s_setprio 0
	s_setprio 1
	v_mfma_f32_16x16x32_bf16 v[24:27], v[202:205], v[68:71], v[24:27]
	v_mfma_f32_16x16x32_bf16 v[20:23], v[104:107], v[84:87], v[20:23]
	v_mfma_f32_16x16x32_bf16 v[28:31], v[104:107], v[68:71], v[28:31]
	v_mfma_f32_16x16x32_bf16 v[24:27], v[206:209], v[76:79], v[24:27]
	v_mfma_f32_16x16x32_bf16 v[20:23], v[192:195], v[168:171], v[20:23]
	v_mfma_f32_16x16x32_bf16 v[16:19], v[202:205], v[84:87], v[16:19]
	v_mfma_f32_16x16x32_bf16 v[12:15], v[104:107], v[172:175], v[12:15]
	v_mfma_f32_16x16x32_bf16 v[8:11], v[202:205], v[172:175], v[8:11]
	v_mfma_f32_16x16x32_bf16 v[4:7], v[104:107], v[180:183], v[4:7]
	v_mfma_f32_16x16x32_bf16 v[0:3], v[202:205], v[180:183], v[0:3]
	v_mfma_f32_16x16x32_bf16 v[142:145], v[192:195], v[76:79], v[28:31]
	v_mfma_f32_16x16x32_bf16 v[146:149], v[206:209], v[168:171], v[16:19]
	v_mfma_f32_16x16x32_bf16 v[150:153], v[192:195], v[176:179], v[12:15]
	v_mfma_f32_16x16x32_bf16 v[168:171], v[206:209], v[176:179], v[8:11]
	v_mfma_f32_16x16x32_bf16 v[172:175], v[192:195], v[184:187], v[4:7]
	v_mfma_f32_16x16x32_bf16 v[176:179], v[206:209], v[184:187], v[0:3]
	s_setprio 0
	s_barrier
	ds_read_b128 v[16:19], v136
	ds_read_b128 v[180:183], v136 offset:1024
	ds_read_b128 v[184:187], v136 offset:2048
	ds_read_b128 v[192:195], v136 offset:3072
	ds_read_b128 v[0:3], v134 offset:32768
	ds_read_b128 v[4:7], v134 offset:33792
	ds_read_b128 v[8:11], v133 offset:32768
	ds_read_b128 v[12:15], v133 offset:33792
	ds_read_b128 v[44:47], v132 offset:32768
	ds_read_b128 v[202:205], v132 offset:33792
	ds_read_b128 v[206:209], v131 offset:32768
	ds_read_b128 v[222:225], v131 offset:33792
	s_waitcnt vmcnt(2)
	s_barrier
	s_waitcnt lgkmcnt(0)
	s_setprio 1
	s_waitcnt lgkmcnt(0)
	v_mfma_f32_16x16x32_bf16 v[28:31], v[16:19], v[0:3], v[124:127]
	v_mfma_f32_16x16x32_bf16 v[52:55], v[180:183], v[4:7], v[28:31]
	v_mfma_f32_16x16x32_bf16 v[28:31], v[184:187], v[0:3], v[120:123]
	v_mfma_f32_16x16x32_bf16 v[104:107], v[192:195], v[4:7], v[28:31]
	v_mfma_f32_16x16x32_bf16 v[28:31], v[16:19], v[8:11], v[116:119]
	v_mfma_f32_16x16x32_bf16 v[68:71], v[180:183], v[12:15], v[28:31]
	v_mfma_f32_16x16x32_bf16 v[28:31], v[184:187], v[8:11], v[112:115]
	v_mfma_f32_16x16x32_bf16 v[116:119], v[192:195], v[12:15], v[28:31]
	v_mfma_f32_16x16x32_bf16 v[28:31], v[16:19], v[44:47], v[108:111]
	v_mfma_f32_16x16x32_bf16 v[76:79], v[180:183], v[202:205], v[28:31]
	v_mfma_f32_16x16x32_bf16 v[28:31], v[184:187], v[44:47], v[188:191]
	v_mfma_f32_16x16x32_bf16 v[108:111], v[192:195], v[202:205], v[28:31]
	v_mfma_f32_16x16x32_bf16 v[28:31], v[16:19], v[206:209], v[100:103]
	v_mfma_f32_16x16x32_bf16 v[84:87], v[180:183], v[222:225], v[28:31]
	v_mfma_f32_16x16x32_bf16 v[28:31], v[184:187], v[206:209], v[96:99]
	v_mfma_f32_16x16x32_bf16 v[96:99], v[192:195], v[222:225], v[28:31]
	s_setprio 0
	s_barrier
	ds_read_b128 v[188:191], v135
	ds_read_b128 v[228:231], v135 offset:1024
	ds_read_b128 v[232:235], v135 offset:2048
	ds_read_b128 v[236:239], v135 offset:3072
	s_waitcnt vmcnt(0)
	s_barrier
	s_waitcnt lgkmcnt(0)
	s_setprio 1
	s_waitcnt lgkmcnt(0)
	v_mfma_f32_16x16x32_bf16 v[28:31], v[188:191], v[0:3], v[92:95]
	v_mfma_f32_16x16x32_bf16 v[0:3], v[232:235], v[0:3], v[88:91]
	v_mfma_f32_16x16x32_bf16 v[28:31], v[228:231], v[4:7], v[28:31]
	v_mfma_f32_16x16x32_bf16 v[0:3], v[236:239], v[4:7], v[0:3]
	v_mfma_f32_16x16x32_bf16 v[4:7], v[188:191], v[8:11], v[156:159]
	v_mfma_f32_16x16x32_bf16 v[36:39], v[228:231], v[12:15], v[4:7]
	v_mfma_f32_16x16x32_bf16 v[4:7], v[232:235], v[8:11], v[80:83]
	v_mfma_f32_16x16x32_bf16 v[4:7], v[236:239], v[12:15], v[4:7]
	v_mfma_f32_16x16x32_bf16 v[8:11], v[188:191], v[44:47], v[160:163]
	v_mfma_f32_16x16x32_bf16 v[12:15], v[188:191], v[206:209], v[164:167]
	v_mfma_f32_16x16x32_bf16 v[40:43], v[228:231], v[202:205], v[8:11]
	v_mfma_f32_16x16x32_bf16 v[8:11], v[232:235], v[44:47], v[72:75]
	v_mfma_f32_16x16x32_bf16 v[44:47], v[228:231], v[222:225], v[12:15]
	v_mfma_f32_16x16x32_bf16 v[12:15], v[232:235], v[206:209], v[64:67]
	v_mfma_f32_16x16x32_bf16 v[8:11], v[236:239], v[202:205], v[8:11]
	v_mfma_f32_16x16x32_bf16 v[12:15], v[236:239], v[222:225], v[12:15]
	s_setprio 0
	s_barrier
	ds_read_b128 v[64:67], v134 offset:49152
	ds_read_b128 v[134:137], v134 offset:50176
	ds_read_b128 v[154:157], v133 offset:49152
	ds_read_b128 v[158:161], v133 offset:50176
	ds_read_b128 v[162:165], v132 offset:49152
	ds_read_b128 v[202:205], v132 offset:50176
	ds_read_b128 v[206:209], v131 offset:49152
	ds_read_b128 v[130:133], v131 offset:50176
	s_barrier
	s_waitcnt lgkmcnt(0)
	s_setprio 1
	s_waitcnt lgkmcnt(0)
	v_mfma_f32_16x16x32_bf16 v[56:59], v[184:187], v[64:67], v[56:59]
	v_mfma_f32_16x16x32_bf16 v[48:51], v[184:187], v[154:157], v[48:51]
	v_mfma_f32_16x16x32_bf16 v[60:63], v[16:19], v[64:67], v[60:63]
	v_mfma_f32_16x16x32_bf16 v[92:95], v[192:195], v[134:137], v[56:59]
	v_mfma_f32_16x16x32_bf16 v[56:59], v[16:19], v[154:157], v[210:213]
	v_mfma_f32_16x16x32_bf16 v[88:91], v[192:195], v[158:161], v[48:51]
	v_mfma_f32_16x16x32_bf16 v[48:51], v[16:19], v[162:165], v[214:217]
	v_mfma_f32_16x16x32_bf16 v[16:19], v[16:19], v[206:209], v[138:141]
	v_mfma_f32_16x16x32_bf16 v[120:123], v[180:183], v[202:205], v[48:51]
	v_mfma_f32_16x16x32_bf16 v[48:51], v[184:187], v[162:165], v[218:221]
	v_mfma_f32_16x16x32_bf16 v[124:127], v[180:183], v[130:133], v[16:19]
	v_mfma_f32_16x16x32_bf16 v[16:19], v[184:187], v[206:209], v[32:35]
	v_mfma_f32_16x16x32_bf16 v[100:103], v[180:183], v[134:137], v[60:63]
	v_mfma_f32_16x16x32_bf16 v[112:115], v[180:183], v[158:161], v[56:59]
	v_mfma_f32_16x16x32_bf16 v[80:83], v[192:195], v[202:205], v[48:51]
	v_mfma_f32_16x16x32_bf16 v[72:75], v[192:195], v[130:133], v[16:19]
	s_setprio 0
	s_setprio 1
	v_mfma_f32_16x16x32_bf16 v[16:19], v[188:191], v[64:67], v[142:145]
	v_mfma_f32_16x16x32_bf16 v[48:51], v[228:231], v[134:137], v[16:19]
	v_mfma_f32_16x16x32_bf16 v[16:19], v[232:235], v[64:67], v[24:27]
	v_mfma_f32_16x16x32_bf16 v[20:23], v[188:191], v[154:157], v[20:23]
	v_mfma_f32_16x16x32_bf16 v[24:27], v[188:191], v[162:165], v[150:153]
	v_mfma_f32_16x16x32_bf16 v[32:35], v[188:191], v[206:209], v[172:175]
	v_mfma_f32_16x16x32_bf16 v[56:59], v[228:231], v[158:161], v[20:23]
	v_mfma_f32_16x16x32_bf16 v[20:23], v[232:235], v[154:157], v[146:149]
	v_mfma_f32_16x16x32_bf16 v[60:63], v[228:231], v[202:205], v[24:27]
	v_mfma_f32_16x16x32_bf16 v[24:27], v[232:235], v[162:165], v[168:171]
	v_mfma_f32_16x16x32_bf16 v[64:67], v[228:231], v[130:133], v[32:35]
	v_mfma_f32_16x16x32_bf16 v[32:35], v[232:235], v[206:209], v[176:179]
	v_mfma_f32_16x16x32_bf16 v[16:19], v[236:239], v[134:137], v[16:19]
	v_mfma_f32_16x16x32_bf16 v[20:23], v[236:239], v[158:161], v[20:23]
	v_mfma_f32_16x16x32_bf16 v[24:27], v[236:239], v[202:205], v[24:27]
	v_mfma_f32_16x16x32_bf16 v[32:35], v[236:239], v[130:133], v[32:35]
	s_setprio 0
	s_movk_i32 s4, 0x100
	v_cmp_gt_u32_e32 vcc, s4, v128
	s_barrier
	s_and_saveexec_b64 s[4:5], vcc
	s_cbranch_execz .LBB0_95
	s_barrier
	s_branch .LBB0_95

.LBB0_192:
	ds_read_b128 v[140:143], v129
	ds_read_b128 v[144:147], v129 offset:1024
	ds_read_b128 v[148:151], v129 offset:2048
	ds_read_b128 v[152:155], v129 offset:3072
	s_add_u32 s28, s56, s4
	s_addc_u32 s29, s57, s5
	s_add_i32 s40, s52, 0xc000
	s_mov_b32 m0, s40
	s_add_i32 s39, s52, 0xe000
	s_add_u32 s98, s28, s44
	s_addc_u32 s99, s29, s45
	global_load_lds_dwordx4 v128, s[98:99]
	s_mov_b32 m0, s39
	s_nop 0
	global_load_lds_dwordx4 v130, s[98:99]
	ds_read_b128 v[156:159], v136
	ds_read_b128 v[160:163], v136 offset:1024
	ds_read_b128 v[164:167], v135
	ds_read_b128 v[168:171], v135 offset:1024
	ds_read_b128 v[172:175], v134
	ds_read_b128 v[176:179], v134 offset:1024
	ds_read_b128 v[180:183], v133
	ds_read_b128 v[184:187], v133 offset:1024
	s_waitcnt lgkmcnt(8)
	s_barrier
	s_waitcnt lgkmcnt(7)
	v_mfma_f32_16x16x32_bf16 v[124:127], v[140:143], v[156:159], v[124:127]
	v_mfma_f32_16x16x32_bf16 v[120:123], v[148:151], v[156:159], v[120:123]
	s_waitcnt lgkmcnt(5)
	v_mfma_f32_16x16x32_bf16 v[116:119], v[140:143], v[164:167], v[116:119]
	v_mfma_f32_16x16x32_bf16 v[112:115], v[148:151], v[164:167], v[112:115]
	s_waitcnt lgkmcnt(3)
	v_mfma_f32_16x16x32_bf16 v[108:111], v[140:143], v[172:175], v[108:111]
	v_mfma_f32_16x16x32_bf16 v[104:107], v[148:151], v[172:175], v[104:107]
	s_waitcnt lgkmcnt(1)
	v_mfma_f32_16x16x32_bf16 v[100:103], v[140:143], v[180:183], v[100:103]
	v_mfma_f32_16x16x32_bf16 v[96:99], v[148:151], v[180:183], v[96:99]
	v_mfma_f32_16x16x32_bf16 v[124:127], v[144:147], v[160:163], v[124:127]
	v_mfma_f32_16x16x32_bf16 v[120:123], v[152:155], v[160:163], v[120:123]
	v_mfma_f32_16x16x32_bf16 v[116:119], v[144:147], v[168:171], v[116:119]
	v_mfma_f32_16x16x32_bf16 v[112:115], v[152:155], v[168:171], v[112:115]
	v_mfma_f32_16x16x32_bf16 v[108:111], v[144:147], v[176:179], v[108:111]
	v_mfma_f32_16x16x32_bf16 v[104:107], v[152:155], v[176:179], v[104:107]
	s_waitcnt lgkmcnt(0)
	v_mfma_f32_16x16x32_bf16 v[100:103], v[144:147], v[184:187], v[100:103]
	v_mfma_f32_16x16x32_bf16 v[96:99], v[152:155], v[184:187], v[96:99]
	s_barrier
	s_add_u32 s58, s56, s36
	s_addc_u32 s59, s57, s37
	ds_read_b128 v[188:191], v139
	ds_read_b128 v[192:195], v139 offset:1024
	ds_read_b128 v[202:205], v139 offset:2048
	ds_read_b128 v[206:209], v139 offset:3072
	s_add_i32 m0, s52, 0x10000
	s_add_u32 s98, s58, s46
	s_addc_u32 s99, s59, s47
	global_load_lds_dwordx4 v128, s[98:99]
	s_add_i32 m0, s52, 0x12000
	s_nop 0
	global_load_lds_dwordx4 v130, s[98:99]
	s_barrier
	s_waitcnt lgkmcnt(3)
	v_mfma_f32_16x16x32_bf16 v[92:95], v[188:191], v[156:159], v[92:95]
	s_waitcnt lgkmcnt(1)
	v_mfma_f32_16x16x32_bf16 v[88:91], v[202:205], v[156:159], v[88:91]
	v_mfma_f32_16x16x32_bf16 v[84:87], v[188:191], v[164:167], v[84:87]
	v_mfma_f32_16x16x32_bf16 v[80:83], v[202:205], v[164:167], v[80:83]
	v_mfma_f32_16x16x32_bf16 v[76:79], v[188:191], v[172:175], v[76:79]
	v_mfma_f32_16x16x32_bf16 v[72:75], v[202:205], v[172:175], v[72:75]
	v_mfma_f32_16x16x32_bf16 v[68:71], v[188:191], v[180:183], v[68:71]
	v_mfma_f32_16x16x32_bf16 v[64:67], v[202:205], v[180:183], v[64:67]
	v_mfma_f32_16x16x32_bf16 v[92:95], v[192:195], v[160:163], v[92:95]
	s_waitcnt lgkmcnt(0)
	v_mfma_f32_16x16x32_bf16 v[88:91], v[206:209], v[160:163], v[88:91]
	v_mfma_f32_16x16x32_bf16 v[84:87], v[192:195], v[168:171], v[84:87]
	v_mfma_f32_16x16x32_bf16 v[80:83], v[206:209], v[168:171], v[80:83]
	v_mfma_f32_16x16x32_bf16 v[76:79], v[192:195], v[176:179], v[76:79]
	v_mfma_f32_16x16x32_bf16 v[72:75], v[206:209], v[176:179], v[72:75]
	v_mfma_f32_16x16x32_bf16 v[68:71], v[192:195], v[184:187], v[68:71]
	v_mfma_f32_16x16x32_bf16 v[64:67], v[206:209], v[184:187], v[64:67]
	s_barrier
	ds_read_b128 v[156:159], v136 offset:16384
	ds_read_b128 v[160:163], v136 offset:17408
	ds_read_b128 v[164:167], v135 offset:16384
	ds_read_b128 v[168:171], v135 offset:17408
	ds_read_b128 v[172:175], v134 offset:16384
	ds_read_b128 v[176:179], v134 offset:17408
	ds_read_b128 v[180:183], v133 offset:16384
	ds_read_b128 v[184:187], v133 offset:17408
	s_mov_b32 m0, s52
	s_add_u32 s98, s28, s48
	s_addc_u32 s99, s29, s49
	global_load_lds_dwordx4 v128, s[98:99]
	s_add_i32 m0, s52, 0x2000
	s_nop 0
	global_load_lds_dwordx4 v130, s[98:99]
	s_barrier
	s_waitcnt lgkmcnt(7)
	v_mfma_f32_16x16x32_bf16 v[60:63], v[140:143], v[156:159], v[60:63]
	v_mfma_f32_16x16x32_bf16 v[56:59], v[148:151], v[156:159], v[56:59]
	s_waitcnt lgkmcnt(5)
	v_mfma_f32_16x16x32_bf16 v[52:55], v[140:143], v[164:167], v[52:55]
	v_mfma_f32_16x16x32_bf16 v[48:51], v[148:151], v[164:167], v[48:51]
	s_waitcnt lgkmcnt(3)
	v_mfma_f32_16x16x32_bf16 v[44:47], v[140:143], v[172:175], v[44:47]
	v_mfma_f32_16x16x32_bf16 v[40:43], v[148:151], v[172:175], v[40:43]
	s_waitcnt lgkmcnt(1)
	v_mfma_f32_16x16x32_bf16 v[36:39], v[140:143], v[180:183], v[36:39]
	v_mfma_f32_16x16x32_bf16 v[32:35], v[148:151], v[180:183], v[32:35]
	v_mfma_f32_16x16x32_bf16 v[60:63], v[144:147], v[160:163], v[60:63]
	v_mfma_f32_16x16x32_bf16 v[56:59], v[152:155], v[160:163], v[56:59]
	v_mfma_f32_16x16x32_bf16 v[52:55], v[144:147], v[168:171], v[52:55]
	v_mfma_f32_16x16x32_bf16 v[48:51], v[152:155], v[168:171], v[48:51]
	v_mfma_f32_16x16x32_bf16 v[44:47], v[144:147], v[176:179], v[44:47]
	v_mfma_f32_16x16x32_bf16 v[40:43], v[152:155], v[176:179], v[40:43]
	s_waitcnt lgkmcnt(0)
	v_mfma_f32_16x16x32_bf16 v[36:39], v[144:147], v[184:187], v[36:39]
	v_mfma_f32_16x16x32_bf16 v[32:35], v[152:155], v[184:187], v[32:35]
	s_barrier
	s_add_i32 m0, s52, 0x14000
	s_add_u32 s98, s58, s50
	s_addc_u32 s99, s59, s51
	global_load_lds_dwordx4 v128, s[98:99]
	s_add_i32 m0, s52, 0x16000
	s_nop 0
	global_load_lds_dwordx4 v130, s[98:99]
	s_waitcnt vmcnt(6)
	s_barrier
	v_mfma_f32_16x16x32_bf16 v[28:31], v[188:191], v[156:159], v[28:31]
	v_mfma_f32_16x16x32_bf16 v[24:27], v[202:205], v[156:159], v[24:27]
	v_mfma_f32_16x16x32_bf16 v[20:23], v[188:191], v[164:167], v[20:23]
	v_mfma_f32_16x16x32_bf16 v[16:19], v[202:205], v[164:167], v[16:19]
	v_mfma_f32_16x16x32_bf16 v[12:15], v[188:191], v[172:175], v[12:15]
	v_mfma_f32_16x16x32_bf16 v[8:11], v[202:205], v[172:175], v[8:11]
	v_mfma_f32_16x16x32_bf16 v[4:7], v[188:191], v[180:183], v[4:7]
	v_mfma_f32_16x16x32_bf16 v[0:3], v[202:205], v[180:183], v[0:3]
	v_mfma_f32_16x16x32_bf16 v[28:31], v[192:195], v[160:163], v[28:31]
	v_mfma_f32_16x16x32_bf16 v[24:27], v[206:209], v[160:163], v[24:27]
	v_mfma_f32_16x16x32_bf16 v[20:23], v[192:195], v[168:171], v[20:23]
	v_mfma_f32_16x16x32_bf16 v[16:19], v[206:209], v[168:171], v[16:19]
	v_mfma_f32_16x16x32_bf16 v[12:15], v[192:195], v[176:179], v[12:15]
	v_mfma_f32_16x16x32_bf16 v[8:11], v[206:209], v[176:179], v[8:11]
	v_mfma_f32_16x16x32_bf16 v[4:7], v[192:195], v[184:187], v[4:7]
	v_mfma_f32_16x16x32_bf16 v[0:3], v[206:209], v[184:187], v[0:3]
	s_barrier
	ds_read_b128 v[140:143], v138
	ds_read_b128 v[144:147], v138 offset:1024
	ds_read_b128 v[148:151], v138 offset:2048
	ds_read_b128 v[152:155], v138 offset:3072
	s_add_i32 m0, s52, 0x4000
	s_add_u32 s98, s28, s54
	s_addc_u32 s99, s29, s55
	global_load_lds_dwordx4 v128, s[98:99]
	s_add_i32 m0, s52, 0x6000
	s_nop 0
	global_load_lds_dwordx4 v130, s[98:99]
	ds_read_b128 v[156:159], v136 offset:32768
	ds_read_b128 v[160:163], v136 offset:33792
	ds_read_b128 v[164:167], v135 offset:32768
	ds_read_b128 v[168:171], v135 offset:33792
	ds_read_b128 v[172:175], v134 offset:32768
	ds_read_b128 v[176:179], v134 offset:33792
	ds_read_b128 v[180:183], v133 offset:32768
	ds_read_b128 v[184:187], v133 offset:33792
	s_waitcnt lgkmcnt(8)
	s_barrier
	s_waitcnt lgkmcnt(7)
	v_mfma_f32_16x16x32_bf16 v[124:127], v[140:143], v[156:159], v[124:127]
	v_mfma_f32_16x16x32_bf16 v[120:123], v[148:151], v[156:159], v[120:123]
	s_waitcnt lgkmcnt(5)
	v_mfma_f32_16x16x32_bf16 v[116:119], v[140:143], v[164:167], v[116:119]
	v_mfma_f32_16x16x32_bf16 v[112:115], v[148:151], v[164:167], v[112:115]
	s_waitcnt lgkmcnt(3)
	v_mfma_f32_16x16x32_bf16 v[108:111], v[140:143], v[172:175], v[108:111]
	v_mfma_f32_16x16x32_bf16 v[104:107], v[148:151], v[172:175], v[104:107]
	s_waitcnt lgkmcnt(1)
	v_mfma_f32_16x16x32_bf16 v[100:103], v[140:143], v[180:183], v[100:103]
	v_mfma_f32_16x16x32_bf16 v[96:99], v[148:151], v[180:183], v[96:99]
	v_mfma_f32_16x16x32_bf16 v[124:127], v[144:147], v[160:163], v[124:127]
	v_mfma_f32_16x16x32_bf16 v[120:123], v[152:155], v[160:163], v[120:123]
	v_mfma_f32_16x16x32_bf16 v[116:119], v[144:147], v[168:171], v[116:119]
	v_mfma_f32_16x16x32_bf16 v[112:115], v[152:155], v[168:171], v[112:115]
	v_mfma_f32_16x16x32_bf16 v[108:111], v[144:147], v[176:179], v[108:111]
	v_mfma_f32_16x16x32_bf16 v[104:107], v[152:155], v[176:179], v[104:107]
	s_waitcnt lgkmcnt(0)
	v_mfma_f32_16x16x32_bf16 v[100:103], v[144:147], v[184:187], v[100:103]
	v_mfma_f32_16x16x32_bf16 v[96:99], v[152:155], v[184:187], v[96:99]
	s_barrier
	ds_read_b128 v[188:191], v137
	ds_read_b128 v[192:195], v137 offset:1024
	ds_read_b128 v[202:205], v137 offset:2048
	ds_read_b128 v[206:209], v137 offset:3072
	s_mov_b32 m0, s7
	s_add_u32 s98, s58, s68
	s_addc_u32 s99, s59, s69
	global_load_lds_dwordx4 v128, s[98:99]
	s_mov_b32 m0, s53
	s_nop 0
	global_load_lds_dwordx4 v130, s[98:99]
	s_barrier
	s_waitcnt lgkmcnt(3)
	v_mfma_f32_16x16x32_bf16 v[92:95], v[188:191], v[156:159], v[92:95]
	s_waitcnt lgkmcnt(1)
	v_mfma_f32_16x16x32_bf16 v[88:91], v[202:205], v[156:159], v[88:91]
	v_mfma_f32_16x16x32_bf16 v[84:87], v[188:191], v[164:167], v[84:87]
	v_mfma_f32_16x16x32_bf16 v[80:83], v[202:205], v[164:167], v[80:83]
	v_mfma_f32_16x16x32_bf16 v[76:79], v[188:191], v[172:175], v[76:79]
	v_mfma_f32_16x16x32_bf16 v[72:75], v[202:205], v[172:175], v[72:75]
	v_mfma_f32_16x16x32_bf16 v[68:71], v[188:191], v[180:183], v[68:71]
	v_mfma_f32_16x16x32_bf16 v[64:67], v[202:205], v[180:183], v[64:67]
	v_mfma_f32_16x16x32_bf16 v[92:95], v[192:195], v[160:163], v[92:95]
	s_waitcnt lgkmcnt(0)
	v_mfma_f32_16x16x32_bf16 v[88:91], v[206:209], v[160:163], v[88:91]
	v_mfma_f32_16x16x32_bf16 v[84:87], v[192:195], v[168:171], v[84:87]
	v_mfma_f32_16x16x32_bf16 v[80:83], v[206:209], v[168:171], v[80:83]
	v_mfma_f32_16x16x32_bf16 v[76:79], v[192:195], v[176:179], v[76:79]
	v_mfma_f32_16x16x32_bf16 v[72:75], v[206:209], v[176:179], v[72:75]
	v_mfma_f32_16x16x32_bf16 v[68:71], v[192:195], v[184:187], v[68:71]
	v_mfma_f32_16x16x32_bf16 v[64:67], v[206:209], v[184:187], v[64:67]
	v_mov_b32_e32 v210, v130
	s_barrier
	ds_read_b128 v[156:159], v136 offset:49152
	ds_read_b128 v[160:163], v136 offset:50176
	ds_read_b128 v[164:167], v135 offset:49152
	ds_read_b128 v[168:171], v135 offset:50176
	ds_read_b128 v[172:175], v134 offset:49152
	ds_read_b128 v[176:179], v134 offset:50176
	ds_read_b128 v[180:183], v133 offset:49152
	ds_read_b128 v[184:187], v133 offset:50176
	v_mov_b32_e32 v211, v197
	s_mov_b32 m0, s9
	s_add_u32 s98, s28, s70
	s_addc_u32 s99, s29, s71
	global_load_lds_dwordx4 v128, s[98:99]
	s_mov_b32 m0, s33
	s_nop 0
	global_load_lds_dwordx4 v130, s[98:99]
	s_barrier
	s_waitcnt lgkmcnt(7)
	v_mfma_f32_16x16x32_bf16 v[60:63], v[140:143], v[156:159], v[60:63]
	v_mfma_f32_16x16x32_bf16 v[56:59], v[148:151], v[156:159], v[56:59]
	s_waitcnt lgkmcnt(5)
	v_mfma_f32_16x16x32_bf16 v[52:55], v[140:143], v[164:167], v[52:55]
	v_mfma_f32_16x16x32_bf16 v[48:51], v[148:151], v[164:167], v[48:51]
	s_waitcnt lgkmcnt(3)
	v_mfma_f32_16x16x32_bf16 v[44:47], v[140:143], v[172:175], v[44:47]
	v_mfma_f32_16x16x32_bf16 v[40:43], v[148:151], v[172:175], v[40:43]
	s_waitcnt lgkmcnt(1)
	v_mfma_f32_16x16x32_bf16 v[36:39], v[140:143], v[180:183], v[36:39]
	v_mfma_f32_16x16x32_bf16 v[32:35], v[148:151], v[180:183], v[32:35]
	v_mfma_f32_16x16x32_bf16 v[60:63], v[144:147], v[160:163], v[60:63]
	v_mfma_f32_16x16x32_bf16 v[56:59], v[152:155], v[160:163], v[56:59]
	v_mfma_f32_16x16x32_bf16 v[52:55], v[144:147], v[168:171], v[52:55]
	v_mfma_f32_16x16x32_bf16 v[48:51], v[152:155], v[168:171], v[48:51]
	v_mfma_f32_16x16x32_bf16 v[44:47], v[144:147], v[176:179], v[44:47]
	v_mfma_f32_16x16x32_bf16 v[40:43], v[152:155], v[176:179], v[40:43]
	s_waitcnt lgkmcnt(0)
	v_mfma_f32_16x16x32_bf16 v[36:39], v[144:147], v[184:187], v[36:39]
	v_mfma_f32_16x16x32_bf16 v[32:35], v[152:155], v[184:187], v[32:35]
	s_barrier
	v_mov_b32_e32 v196, v128
	s_mov_b32 m0, s65
	s_add_u32 s98, s58, s72
	s_addc_u32 s99, s59, s73
	global_load_lds_dwordx4 v128, s[98:99]
	s_mov_b32 m0, s66
	s_nop 0
	global_load_lds_dwordx4 v130, s[98:99]
	s_waitcnt vmcnt(6)
	s_barrier
	v_mfma_f32_16x16x32_bf16 v[28:31], v[188:191], v[156:159], v[28:31]
	v_mfma_f32_16x16x32_bf16 v[24:27], v[202:205], v[156:159], v[24:27]
	v_mfma_f32_16x16x32_bf16 v[20:23], v[188:191], v[164:167], v[20:23]
	v_mfma_f32_16x16x32_bf16 v[16:19], v[202:205], v[164:167], v[16:19]
	v_mfma_f32_16x16x32_bf16 v[12:15], v[188:191], v[172:175], v[12:15]
	v_mfma_f32_16x16x32_bf16 v[8:11], v[202:205], v[172:175], v[8:11]
	v_mfma_f32_16x16x32_bf16 v[4:7], v[188:191], v[180:183], v[4:7]
	v_mfma_f32_16x16x32_bf16 v[0:3], v[202:205], v[180:183], v[0:3]
	v_mfma_f32_16x16x32_bf16 v[28:31], v[192:195], v[160:163], v[28:31]
	v_mfma_f32_16x16x32_bf16 v[24:27], v[206:209], v[160:163], v[24:27]
	v_mfma_f32_16x16x32_bf16 v[20:23], v[192:195], v[168:171], v[20:23]
	v_mfma_f32_16x16x32_bf16 v[16:19], v[206:209], v[168:171], v[16:19]
	v_mfma_f32_16x16x32_bf16 v[12:15], v[192:195], v[176:179], v[12:15]
	v_mfma_f32_16x16x32_bf16 v[8:11], v[206:209], v[176:179], v[8:11]
	v_mfma_f32_16x16x32_bf16 v[4:7], v[192:195], v[184:187], v[4:7]
	v_mfma_f32_16x16x32_bf16 v[0:3], v[206:209], v[184:187], v[0:3]
	s_add_i32 s38, s38, 2
	s_add_u32 s56, s56, 0x100
	s_addc_u32 s57, s57, 0
	s_cmp_lt_u32 s38, 28
	s_barrier
	s_cbranch_scc1 .LBB0_192
	s_lshl_b64 s[4:5], s[10:11], 12
	v_readlane_b32 s10, v254, 12
	v_readlane_b32 s11, v254, 13
	s_add_u32 s4, s10, s4
	s_addc_u32 s5, s11, s5
	ds_read_b128 v[140:143], v129
	ds_read_b128 v[144:147], v129 offset:1024
	ds_read_b128 v[148:151], v129 offset:2048
	ds_read_b128 v[152:155], v129 offset:3072
	ds_read_b128 v[156:159], v136
	ds_read_b128 v[160:163], v136 offset:1024
	ds_read_b128 v[164:167], v135
	ds_read_b128 v[168:171], v135 offset:1024
	ds_read_b128 v[172:175], v134
	ds_read_b128 v[176:179], v134 offset:1024
	ds_read_b128 v[180:183], v133
	ds_read_b128 v[184:187], v133 offset:1024
	v_mov_b32_e32 v129, v197
	v_lshl_add_u64 v[128:129], s[4:5], 0, v[128:129]
	s_mov_b64 s[10:11], 0xf80
	s_mov_b32 m0, s40
	v_lshl_add_u64 v[128:129], v[128:129], 0, s[10:11]
	v_mov_b32_e32 v131, v197
	global_load_lds_dwordx4 v[128:129], off
	v_lshl_add_u64 v[128:129], s[4:5], 0, v[130:131]
	v_lshl_add_u64 v[128:129], v[128:129], 0, s[10:11]
	s_mov_b32 m0, s39
	s_nop 0
	global_load_lds_dwordx4 v[128:129], off
	s_barrier
	s_waitcnt lgkmcnt(0)
	s_setprio 1
	s_waitcnt lgkmcnt(0)
	v_mfma_f32_16x16x32_bf16 v[124:127], v[140:143], v[156:159], v[124:127]
	v_mfma_f32_16x16x32_bf16 v[116:119], v[140:143], v[164:167], v[116:119]
	v_mfma_f32_16x16x32_bf16 v[112:115], v[148:151], v[164:167], v[112:115]
	v_mfma_f32_16x16x32_bf16 v[108:111], v[140:143], v[172:175], v[108:111]
	v_mfma_f32_16x16x32_bf16 v[104:107], v[148:151], v[172:175], v[104:107]
	v_mfma_f32_16x16x32_bf16 v[100:103], v[140:143], v[180:183], v[100:103]
	v_mfma_f32_16x16x32_bf16 v[96:99], v[148:151], v[180:183], v[96:99]
	v_mfma_f32_16x16x32_bf16 v[124:127], v[144:147], v[160:163], v[124:127]
	v_mfma_f32_16x16x32_bf16 v[120:123], v[148:151], v[156:159], v[120:123]
	v_mfma_f32_16x16x32_bf16 v[116:119], v[144:147], v[168:171], v[116:119]
	v_mfma_f32_16x16x32_bf16 v[112:115], v[152:155], v[168:171], v[112:115]
	v_mfma_f32_16x16x32_bf16 v[108:111], v[144:147], v[176:179], v[108:111]
	v_mfma_f32_16x16x32_bf16 v[104:107], v[152:155], v[176:179], v[104:107]
	v_mfma_f32_16x16x32_bf16 v[100:103], v[144:147], v[184:187], v[100:103]
	v_mfma_f32_16x16x32_bf16 v[96:99], v[152:155], v[184:187], v[96:99]
	v_mfma_f32_16x16x32_bf16 v[128:131], v[152:155], v[160:163], v[120:123]
	s_setprio 0
	s_barrier
	s_nop 0
	ds_read_b128 v[120:123], v139
	ds_read_b128 v[188:191], v139 offset:1024
	ds_read_b128 v[192:195], v139 offset:2048
	ds_read_b128 v[202:205], v139 offset:3072
	s_barrier
	s_waitcnt lgkmcnt(0)
	s_setprio 1
	s_waitcnt lgkmcnt(0)
	v_mfma_f32_16x16x32_bf16 v[76:79], v[120:123], v[172:175], v[76:79]
	v_mfma_f32_16x16x32_bf16 v[68:71], v[120:123], v[180:183], v[68:71]
	v_mfma_f32_16x16x32_bf16 v[64:67], v[192:195], v[180:183], v[64:67]
	v_mfma_f32_16x16x32_bf16 v[92:95], v[120:123], v[156:159], v[92:95]
	v_mfma_f32_16x16x32_bf16 v[88:91], v[192:195], v[156:159], v[88:91]
	v_mfma_f32_16x16x32_bf16 v[84:87], v[120:123], v[164:167], v[84:87]
	v_mfma_f32_16x16x32_bf16 v[80:83], v[192:195], v[164:167], v[80:83]
	v_mfma_f32_16x16x32_bf16 v[76:79], v[188:191], v[176:179], v[76:79]
	v_mfma_f32_16x16x32_bf16 v[72:75], v[192:195], v[172:175], v[72:75]
	v_mfma_f32_16x16x32_bf16 v[68:71], v[188:191], v[184:187], v[68:71]
	v_mfma_f32_16x16x32_bf16 v[64:67], v[202:205], v[184:187], v[64:67]
	v_mfma_f32_16x16x32_bf16 v[206:209], v[188:191], v[160:163], v[92:95]
	v_mfma_f32_16x16x32_bf16 v[156:159], v[202:205], v[160:163], v[88:91]
	v_mfma_f32_16x16x32_bf16 v[160:163], v[188:191], v[168:171], v[84:87]
	v_mfma_f32_16x16x32_bf16 v[164:167], v[202:205], v[168:171], v[80:83]
	v_mfma_f32_16x16x32_bf16 v[168:171], v[202:205], v[176:179], v[72:75]
	s_setprio 0
	s_barrier
	s_nop 0
	ds_read_b128 v[72:75], v136 offset:16384
	ds_read_b128 v[80:83], v136 offset:17408
	ds_read_b128 v[84:87], v135 offset:16384
	ds_read_b128 v[88:91], v135 offset:17408
	ds_read_b128 v[92:95], v134 offset:16384
	ds_read_b128 v[172:175], v134 offset:17408
	ds_read_b128 v[176:179], v133 offset:16384
	ds_read_b128 v[180:183], v133 offset:17408
	s_waitcnt vmcnt(4)
	s_barrier
	s_waitcnt lgkmcnt(0)
	s_setprio 1
	s_waitcnt lgkmcnt(0)
	v_mfma_f32_16x16x32_bf16 v[60:63], v[140:143], v[72:75], v[60:63]
	v_mfma_f32_16x16x32_bf16 v[52:55], v[140:143], v[84:87], v[52:55]
	v_mfma_f32_16x16x32_bf16 v[48:51], v[148:151], v[84:87], v[48:51]
	v_mfma_f32_16x16x32_bf16 v[44:47], v[140:143], v[92:95], v[44:47]
	v_mfma_f32_16x16x32_bf16 v[40:43], v[148:151], v[92:95], v[40:43]
	v_mfma_f32_16x16x32_bf16 v[36:39], v[140:143], v[176:179], v[36:39]
	v_mfma_f32_16x16x32_bf16 v[32:35], v[148:151], v[176:179], v[32:35]
	v_mfma_f32_16x16x32_bf16 v[60:63], v[144:147], v[80:83], v[60:63]
	v_mfma_f32_16x16x32_bf16 v[56:59], v[148:151], v[72:75], v[56:59]
	v_mfma_f32_16x16x32_bf16 v[52:55], v[144:147], v[88:91], v[52:55]
	v_mfma_f32_16x16x32_bf16 v[48:51], v[152:155], v[88:91], v[48:51]
	v_mfma_f32_16x16x32_bf16 v[44:47], v[144:147], v[172:175], v[44:47]
	v_mfma_f32_16x16x32_bf16 v[40:43], v[152:155], v[172:175], v[40:43]
	v_mfma_f32_16x16x32_bf16 v[36:39], v[144:147], v[180:183], v[36:39]
	v_mfma_f32_16x16x32_bf16 v[32:35], v[152:155], v[180:183], v[32:35]
	v_mfma_f32_16x16x32_bf16 v[184:187], v[152:155], v[80:83], v[56:59]
	s_setprio 0
	s_setprio 1
	v_mfma_f32_16x16x32_bf16 v[12:15], v[120:123], v[92:95], v[12:15]
	v_mfma_f32_16x16x32_bf16 v[4:7], v[120:123], v[176:179], v[4:7]
	v_mfma_f32_16x16x32_bf16 v[0:3], v[192:195], v[176:179], v[0:3]
	v_mfma_f32_16x16x32_bf16 v[28:31], v[120:123], v[72:75], v[28:31]
	v_mfma_f32_16x16x32_bf16 v[24:27], v[192:195], v[72:75], v[24:27]
	v_mfma_f32_16x16x32_bf16 v[20:23], v[120:123], v[84:87], v[20:23]
	v_mfma_f32_16x16x32_bf16 v[16:19], v[192:195], v[84:87], v[16:19]
	v_mfma_f32_16x16x32_bf16 v[12:15], v[188:191], v[172:175], v[12:15]
	v_mfma_f32_16x16x32_bf16 v[8:11], v[192:195], v[92:95], v[8:11]
	v_mfma_f32_16x16x32_bf16 v[4:7], v[188:191], v[180:183], v[4:7]
	v_mfma_f32_16x16x32_bf16 v[0:3], v[202:205], v[180:183], v[0:3]
	v_mfma_f32_16x16x32_bf16 v[140:143], v[188:191], v[80:83], v[28:31]
	v_mfma_f32_16x16x32_bf16 v[144:147], v[202:205], v[80:83], v[24:27]
	v_mfma_f32_16x16x32_bf16 v[148:151], v[188:191], v[88:91], v[20:23]
	v_mfma_f32_16x16x32_bf16 v[152:155], v[202:205], v[88:91], v[16:19]
	v_mfma_f32_16x16x32_bf16 v[172:175], v[202:205], v[172:175], v[8:11]
	s_setprio 0
	s_barrier
	s_nop 0
	ds_read_b128 v[8:11], v138
	ds_read_b128 v[16:19], v138 offset:1024
	ds_read_b128 v[176:179], v138 offset:2048
	ds_read_b128 v[180:183], v138 offset:3072
	ds_read_b128 v[20:23], v136 offset:32768
	ds_read_b128 v[24:27], v136 offset:33792
	ds_read_b128 v[28:31], v135 offset:32768
	ds_read_b128 v[56:59], v135 offset:33792
	ds_read_b128 v[188:191], v134 offset:32768
	ds_read_b128 v[192:195], v134 offset:33792
	ds_read_b128 v[202:205], v133 offset:32768
	ds_read_b128 v[210:213], v133 offset:33792
	s_waitcnt vmcnt(2)
	s_barrier
	s_waitcnt lgkmcnt(0)
	s_setprio 1
	s_waitcnt lgkmcnt(0)
	v_mfma_f32_16x16x32_bf16 v[72:75], v[8:11], v[20:23], v[124:127]
	v_mfma_f32_16x16x32_bf16 v[120:123], v[16:19], v[24:27], v[72:75]
	v_mfma_f32_16x16x32_bf16 v[72:75], v[176:179], v[20:23], v[128:131]
	v_mfma_f32_16x16x32_bf16 v[124:127], v[180:183], v[24:27], v[72:75]
	v_mfma_f32_16x16x32_bf16 v[72:75], v[8:11], v[28:31], v[116:119]
	v_mfma_f32_16x16x32_bf16 v[116:119], v[16:19], v[56:59], v[72:75]
	v_mfma_f32_16x16x32_bf16 v[72:75], v[176:179], v[28:31], v[112:115]
	v_mfma_f32_16x16x32_bf16 v[112:115], v[180:183], v[56:59], v[72:75]
	v_mfma_f32_16x16x32_bf16 v[72:75], v[8:11], v[188:191], v[108:111]
	v_mfma_f32_16x16x32_bf16 v[88:91], v[16:19], v[192:195], v[72:75]
	v_mfma_f32_16x16x32_bf16 v[72:75], v[176:179], v[188:191], v[104:107]
	v_mfma_f32_16x16x32_bf16 v[92:95], v[180:183], v[192:195], v[72:75]
	v_mfma_f32_16x16x32_bf16 v[72:75], v[8:11], v[202:205], v[100:103]
	v_mfma_f32_16x16x32_bf16 v[84:87], v[16:19], v[210:213], v[72:75]
	v_mfma_f32_16x16x32_bf16 v[72:75], v[176:179], v[202:205], v[96:99]
	v_mfma_f32_16x16x32_bf16 v[80:83], v[180:183], v[210:213], v[72:75]
	s_setprio 0
	s_barrier
	ds_read_b128 v[128:131], v137
	ds_read_b128 v[214:217], v137 offset:1024
	ds_read_b128 v[218:221], v137 offset:2048
	ds_read_b128 v[222:225], v137 offset:3072
	s_waitcnt vmcnt(0)
	s_barrier
	s_waitcnt lgkmcnt(0)
	s_setprio 1
	s_waitcnt lgkmcnt(0)
	v_mfma_f32_16x16x32_bf16 v[72:75], v[128:131], v[20:23], v[206:209]
	v_mfma_f32_16x16x32_bf16 v[20:23], v[218:221], v[20:23], v[156:159]
	v_mfma_f32_16x16x32_bf16 v[108:111], v[222:225], v[24:27], v[20:23]
	v_mfma_f32_16x16x32_bf16 v[20:23], v[128:131], v[28:31], v[160:163]
	v_mfma_f32_16x16x32_bf16 v[100:103], v[214:217], v[56:59], v[20:23]
	v_mfma_f32_16x16x32_bf16 v[20:23], v[218:221], v[28:31], v[164:167]
	v_mfma_f32_16x16x32_bf16 v[96:99], v[222:225], v[56:59], v[20:23]
	v_mfma_f32_16x16x32_bf16 v[20:23], v[128:131], v[188:191], v[76:79]
	v_mfma_f32_16x16x32_bf16 v[104:107], v[214:217], v[24:27], v[72:75]
	v_mfma_f32_16x16x32_bf16 v[72:75], v[214:217], v[192:195], v[20:23]
	v_mfma_f32_16x16x32_bf16 v[20:23], v[218:221], v[188:191], v[168:171]
	v_mfma_f32_16x16x32_bf16 v[76:79], v[222:225], v[192:195], v[20:23]
	v_mfma_f32_16x16x32_bf16 v[20:23], v[128:131], v[202:205], v[68:71]
	v_mfma_f32_16x16x32_bf16 v[68:71], v[214:217], v[210:213], v[20:23]
	v_mfma_f32_16x16x32_bf16 v[20:23], v[218:221], v[202:205], v[64:67]
	v_mfma_f32_16x16x32_bf16 v[64:67], v[222:225], v[210:213], v[20:23]
	s_setprio 0
	s_barrier
	ds_read_b128 v[156:159], v136 offset:49152
	ds_read_b128 v[136:139], v136 offset:50176
	ds_read_b128 v[160:163], v135 offset:49152
	ds_read_b128 v[164:167], v135 offset:50176
	ds_read_b128 v[168:171], v134 offset:49152
	ds_read_b128 v[188:191], v134 offset:50176
	ds_read_b128 v[192:195], v133 offset:49152
	ds_read_b128 v[202:205], v133 offset:50176
	s_barrier
	s_waitcnt lgkmcnt(0)
	s_setprio 1
	s_waitcnt lgkmcnt(0)
	v_mfma_f32_16x16x32_bf16 v[20:23], v[8:11], v[156:159], v[60:63]
	v_mfma_f32_16x16x32_bf16 v[56:59], v[16:19], v[136:139], v[20:23]
	v_mfma_f32_16x16x32_bf16 v[20:23], v[176:179], v[156:159], v[184:187]
	v_mfma_f32_16x16x32_bf16 v[60:63], v[180:183], v[136:139], v[20:23]
	v_mfma_f32_16x16x32_bf16 v[20:23], v[8:11], v[160:163], v[52:55]
	v_mfma_f32_16x16x32_bf16 v[52:55], v[16:19], v[164:167], v[20:23]
	v_mfma_f32_16x16x32_bf16 v[20:23], v[176:179], v[160:163], v[48:51]
	v_mfma_f32_16x16x32_bf16 v[48:51], v[180:183], v[164:167], v[20:23]
	v_mfma_f32_16x16x32_bf16 v[20:23], v[8:11], v[168:171], v[44:47]
	v_mfma_f32_16x16x32_bf16 v[24:27], v[16:19], v[188:191], v[20:23]
	v_mfma_f32_16x16x32_bf16 v[20:23], v[176:179], v[168:171], v[40:43]
	v_mfma_f32_16x16x32_bf16 v[8:11], v[8:11], v[192:195], v[36:39]
	v_mfma_f32_16x16x32_bf16 v[28:31], v[180:183], v[188:191], v[20:23]
	v_mfma_f32_16x16x32_bf16 v[20:23], v[16:19], v[202:205], v[8:11]
	v_mfma_f32_16x16x32_bf16 v[8:11], v[176:179], v[192:195], v[32:35]
	v_mfma_f32_16x16x32_bf16 v[16:19], v[180:183], v[202:205], v[8:11]
	s_setprio 0
	s_setprio 1
	v_mfma_f32_16x16x32_bf16 v[8:11], v[128:131], v[156:159], v[140:143]
	v_mfma_f32_16x16x32_bf16 v[40:43], v[214:217], v[136:139], v[8:11]
	v_mfma_f32_16x16x32_bf16 v[8:11], v[218:221], v[156:159], v[144:147]
	v_mfma_f32_16x16x32_bf16 v[44:47], v[222:225], v[136:139], v[8:11]
	v_mfma_f32_16x16x32_bf16 v[8:11], v[128:131], v[160:163], v[148:151]
	v_mfma_f32_16x16x32_bf16 v[36:39], v[214:217], v[164:167], v[8:11]
	v_mfma_f32_16x16x32_bf16 v[8:11], v[218:221], v[160:163], v[152:155]
	v_mfma_f32_16x16x32_bf16 v[32:35], v[222:225], v[164:167], v[8:11]
	v_mfma_f32_16x16x32_bf16 v[8:11], v[128:131], v[168:171], v[12:15]
	v_mfma_f32_16x16x32_bf16 v[12:15], v[218:221], v[168:171], v[172:175]
	v_mfma_f32_16x16x32_bf16 v[4:7], v[128:131], v[192:195], v[4:7]
	v_mfma_f32_16x16x32_bf16 v[0:3], v[218:221], v[192:195], v[0:3]
	v_mfma_f32_16x16x32_bf16 v[8:11], v[214:217], v[188:191], v[8:11]
	v_mfma_f32_16x16x32_bf16 v[12:15], v[222:225], v[188:191], v[12:15]
	v_mfma_f32_16x16x32_bf16 v[4:7], v[214:217], v[202:205], v[4:7]
	v_mfma_f32_16x16x32_bf16 v[0:3], v[222:225], v[202:205], v[0:3]
	s_setprio 0
	s_movk_i32 s4, 0x100
	v_cmp_gt_u32_e32 vcc, s4, v132
	s_barrier
	s_and_saveexec_b64 s[4:5], vcc
	s_cbranch_execz .LBB0_195
	s_barrier

.LBB0_255:
	ds_read_b128 v[140:143], v129
	ds_read_b128 v[144:147], v129 offset:1024
	ds_read_b128 v[148:151], v129 offset:2048
	ds_read_b128 v[152:155], v129 offset:3072
	s_add_u32 s28, s60, s56
	s_addc_u32 s29, s61, s57
	s_add_i32 s40, s53, 0xc000
	s_mov_b32 m0, s40
	s_add_i32 s39, s53, 0xe000
	s_add_u32 s98, s28, s44
	s_addc_u32 s99, s29, s45
	global_load_lds_dwordx4 v128, s[98:99]
	s_mov_b32 m0, s39
	s_nop 0
	global_load_lds_dwordx4 v130, s[98:99]
	ds_read_b128 v[156:159], v136
	ds_read_b128 v[160:163], v136 offset:1024
	ds_read_b128 v[164:167], v135
	ds_read_b128 v[168:171], v135 offset:1024
	ds_read_b128 v[172:175], v134
	ds_read_b128 v[176:179], v134 offset:1024
	ds_read_b128 v[180:183], v133
	ds_read_b128 v[184:187], v133 offset:1024
	s_waitcnt lgkmcnt(8)
	s_barrier
	s_waitcnt lgkmcnt(7)
	v_mfma_f32_16x16x32_bf16 v[124:127], v[140:143], v[156:159], v[124:127]
	v_mfma_f32_16x16x32_bf16 v[120:123], v[148:151], v[156:159], v[120:123]
	s_waitcnt lgkmcnt(5)
	v_mfma_f32_16x16x32_bf16 v[116:119], v[140:143], v[164:167], v[116:119]
	v_mfma_f32_16x16x32_bf16 v[112:115], v[148:151], v[164:167], v[112:115]
	s_waitcnt lgkmcnt(3)
	v_mfma_f32_16x16x32_bf16 v[108:111], v[140:143], v[172:175], v[108:111]
	v_mfma_f32_16x16x32_bf16 v[104:107], v[148:151], v[172:175], v[104:107]
	s_waitcnt lgkmcnt(1)
	v_mfma_f32_16x16x32_bf16 v[100:103], v[140:143], v[180:183], v[100:103]
	v_mfma_f32_16x16x32_bf16 v[96:99], v[148:151], v[180:183], v[96:99]
	v_mfma_f32_16x16x32_bf16 v[124:127], v[144:147], v[160:163], v[124:127]
	v_mfma_f32_16x16x32_bf16 v[120:123], v[152:155], v[160:163], v[120:123]
	v_mfma_f32_16x16x32_bf16 v[116:119], v[144:147], v[168:171], v[116:119]
	v_mfma_f32_16x16x32_bf16 v[112:115], v[152:155], v[168:171], v[112:115]
	v_mfma_f32_16x16x32_bf16 v[108:111], v[144:147], v[176:179], v[108:111]
	v_mfma_f32_16x16x32_bf16 v[104:107], v[152:155], v[176:179], v[104:107]
	s_waitcnt lgkmcnt(0)
	v_mfma_f32_16x16x32_bf16 v[100:103], v[144:147], v[184:187], v[100:103]
	v_mfma_f32_16x16x32_bf16 v[96:99], v[152:155], v[184:187], v[96:99]
	s_barrier
	s_add_u32 s62, s60, s36
	s_addc_u32 s63, s61, s37
	ds_read_b128 v[188:191], v139
	ds_read_b128 v[192:195], v139 offset:1024
	ds_read_b128 v[202:205], v139 offset:2048
	ds_read_b128 v[206:209], v139 offset:3072
	s_mov_b32 m0, s68
	s_add_u32 s98, s62, s46
	s_addc_u32 s99, s63, s47
	global_load_lds_dwordx4 v128, s[98:99]
	s_mov_b32 m0, s69
	s_nop 0
	global_load_lds_dwordx4 v130, s[98:99]
	s_barrier
	s_waitcnt lgkmcnt(3)
	v_mfma_f32_16x16x32_bf16 v[92:95], v[188:191], v[156:159], v[92:95]
	s_waitcnt lgkmcnt(1)
	v_mfma_f32_16x16x32_bf16 v[88:91], v[202:205], v[156:159], v[88:91]
	v_mfma_f32_16x16x32_bf16 v[84:87], v[188:191], v[164:167], v[84:87]
	v_mfma_f32_16x16x32_bf16 v[80:83], v[202:205], v[164:167], v[80:83]
	v_mfma_f32_16x16x32_bf16 v[76:79], v[188:191], v[172:175], v[76:79]
	v_mfma_f32_16x16x32_bf16 v[72:75], v[202:205], v[172:175], v[72:75]
	v_mfma_f32_16x16x32_bf16 v[68:71], v[188:191], v[180:183], v[68:71]
	v_mfma_f32_16x16x32_bf16 v[64:67], v[202:205], v[180:183], v[64:67]
	v_mfma_f32_16x16x32_bf16 v[92:95], v[192:195], v[160:163], v[92:95]
	s_waitcnt lgkmcnt(0)
	v_mfma_f32_16x16x32_bf16 v[88:91], v[206:209], v[160:163], v[88:91]
	v_mfma_f32_16x16x32_bf16 v[84:87], v[192:195], v[168:171], v[84:87]
	v_mfma_f32_16x16x32_bf16 v[80:83], v[206:209], v[168:171], v[80:83]
	v_mfma_f32_16x16x32_bf16 v[76:79], v[192:195], v[176:179], v[76:79]
	v_mfma_f32_16x16x32_bf16 v[72:75], v[206:209], v[176:179], v[72:75]
	v_mfma_f32_16x16x32_bf16 v[68:71], v[192:195], v[184:187], v[68:71]
	v_mfma_f32_16x16x32_bf16 v[64:67], v[206:209], v[184:187], v[64:67]
	s_barrier
	ds_read_b128 v[156:159], v136 offset:16384
	ds_read_b128 v[160:163], v136 offset:17408
	ds_read_b128 v[164:167], v135 offset:16384
	ds_read_b128 v[168:171], v135 offset:17408
	ds_read_b128 v[172:175], v134 offset:16384
	ds_read_b128 v[176:179], v134 offset:17408
	ds_read_b128 v[180:183], v133 offset:16384
	ds_read_b128 v[184:187], v133 offset:17408
	s_mov_b32 m0, s53
	s_add_u32 s98, s28, s48
	s_addc_u32 s99, s29, s49
	global_load_lds_dwordx4 v128, s[98:99]
	s_mov_b32 m0, s11
	s_nop 0
	global_load_lds_dwordx4 v130, s[98:99]
	s_barrier
	s_waitcnt lgkmcnt(7)
	v_mfma_f32_16x16x32_bf16 v[60:63], v[140:143], v[156:159], v[60:63]
	v_mfma_f32_16x16x32_bf16 v[56:59], v[148:151], v[156:159], v[56:59]
	s_waitcnt lgkmcnt(5)
	v_mfma_f32_16x16x32_bf16 v[52:55], v[140:143], v[164:167], v[52:55]
	v_mfma_f32_16x16x32_bf16 v[48:51], v[148:151], v[164:167], v[48:51]
	s_waitcnt lgkmcnt(3)
	v_mfma_f32_16x16x32_bf16 v[44:47], v[140:143], v[172:175], v[44:47]
	v_mfma_f32_16x16x32_bf16 v[40:43], v[148:151], v[172:175], v[40:43]
	s_waitcnt lgkmcnt(1)
	v_mfma_f32_16x16x32_bf16 v[36:39], v[140:143], v[180:183], v[36:39]
	v_mfma_f32_16x16x32_bf16 v[32:35], v[148:151], v[180:183], v[32:35]
	v_mfma_f32_16x16x32_bf16 v[60:63], v[144:147], v[160:163], v[60:63]
	v_mfma_f32_16x16x32_bf16 v[56:59], v[152:155], v[160:163], v[56:59]
	v_mfma_f32_16x16x32_bf16 v[52:55], v[144:147], v[168:171], v[52:55]
	v_mfma_f32_16x16x32_bf16 v[48:51], v[152:155], v[168:171], v[48:51]
	v_mfma_f32_16x16x32_bf16 v[44:47], v[144:147], v[176:179], v[44:47]
	v_mfma_f32_16x16x32_bf16 v[40:43], v[152:155], v[176:179], v[40:43]
	s_waitcnt lgkmcnt(0)
	v_mfma_f32_16x16x32_bf16 v[36:39], v[144:147], v[184:187], v[36:39]
	v_mfma_f32_16x16x32_bf16 v[32:35], v[152:155], v[184:187], v[32:35]
	s_barrier
	s_mov_b32 m0, s9
	s_add_u32 s98, s62, s50
	s_addc_u32 s99, s63, s51
	global_load_lds_dwordx4 v128, s[98:99]
	s_mov_b32 m0, s70
	s_nop 0
	global_load_lds_dwordx4 v130, s[98:99]
	s_waitcnt vmcnt(6)
	s_barrier
	v_mfma_f32_16x16x32_bf16 v[28:31], v[188:191], v[156:159], v[28:31]
	v_mfma_f32_16x16x32_bf16 v[24:27], v[202:205], v[156:159], v[24:27]
	v_mfma_f32_16x16x32_bf16 v[20:23], v[188:191], v[164:167], v[20:23]
	v_mfma_f32_16x16x32_bf16 v[16:19], v[202:205], v[164:167], v[16:19]
	v_mfma_f32_16x16x32_bf16 v[12:15], v[188:191], v[172:175], v[12:15]
	v_mfma_f32_16x16x32_bf16 v[8:11], v[202:205], v[172:175], v[8:11]
	v_mfma_f32_16x16x32_bf16 v[4:7], v[188:191], v[180:183], v[4:7]
	v_mfma_f32_16x16x32_bf16 v[0:3], v[202:205], v[180:183], v[0:3]
	v_mfma_f32_16x16x32_bf16 v[28:31], v[192:195], v[160:163], v[28:31]
	v_mfma_f32_16x16x32_bf16 v[24:27], v[206:209], v[160:163], v[24:27]
	v_mfma_f32_16x16x32_bf16 v[20:23], v[192:195], v[168:171], v[20:23]
	v_mfma_f32_16x16x32_bf16 v[16:19], v[206:209], v[168:171], v[16:19]
	v_mfma_f32_16x16x32_bf16 v[12:15], v[192:195], v[176:179], v[12:15]
	v_mfma_f32_16x16x32_bf16 v[8:11], v[206:209], v[176:179], v[8:11]
	v_mfma_f32_16x16x32_bf16 v[4:7], v[192:195], v[184:187], v[4:7]
	v_mfma_f32_16x16x32_bf16 v[0:3], v[206:209], v[184:187], v[0:3]
	s_barrier
	ds_read_b128 v[140:143], v138
	ds_read_b128 v[144:147], v138 offset:1024
	ds_read_b128 v[148:151], v138 offset:2048
	ds_read_b128 v[152:155], v138 offset:3072
	s_mov_b32 m0, s71
	s_add_u32 s98, s28, s74
	s_addc_u32 s99, s29, s75
	global_load_lds_dwordx4 v128, s[98:99]
	s_mov_b32 m0, s72
	s_nop 0
	global_load_lds_dwordx4 v130, s[98:99]
	ds_read_b128 v[156:159], v136 offset:32768
	ds_read_b128 v[160:163], v136 offset:33792
	ds_read_b128 v[164:167], v135 offset:32768
	ds_read_b128 v[168:171], v135 offset:33792
	ds_read_b128 v[172:175], v134 offset:32768
	ds_read_b128 v[176:179], v134 offset:33792
	ds_read_b128 v[180:183], v133 offset:32768
	ds_read_b128 v[184:187], v133 offset:33792
	s_waitcnt lgkmcnt(8)
	s_barrier
	s_waitcnt lgkmcnt(7)
	v_mfma_f32_16x16x32_bf16 v[124:127], v[140:143], v[156:159], v[124:127]
	v_mfma_f32_16x16x32_bf16 v[120:123], v[148:151], v[156:159], v[120:123]
	s_waitcnt lgkmcnt(5)
	v_mfma_f32_16x16x32_bf16 v[116:119], v[140:143], v[164:167], v[116:119]
	v_mfma_f32_16x16x32_bf16 v[112:115], v[148:151], v[164:167], v[112:115]
	s_waitcnt lgkmcnt(3)
	v_mfma_f32_16x16x32_bf16 v[108:111], v[140:143], v[172:175], v[108:111]
	v_mfma_f32_16x16x32_bf16 v[104:107], v[148:151], v[172:175], v[104:107]
	s_waitcnt lgkmcnt(1)
	v_mfma_f32_16x16x32_bf16 v[100:103], v[140:143], v[180:183], v[100:103]
	v_mfma_f32_16x16x32_bf16 v[96:99], v[148:151], v[180:183], v[96:99]
	v_mfma_f32_16x16x32_bf16 v[124:127], v[144:147], v[160:163], v[124:127]
	v_mfma_f32_16x16x32_bf16 v[120:123], v[152:155], v[160:163], v[120:123]
	v_mfma_f32_16x16x32_bf16 v[116:119], v[144:147], v[168:171], v[116:119]
	v_mfma_f32_16x16x32_bf16 v[112:115], v[152:155], v[168:171], v[112:115]
	v_mfma_f32_16x16x32_bf16 v[108:111], v[144:147], v[176:179], v[108:111]
	v_mfma_f32_16x16x32_bf16 v[104:107], v[152:155], v[176:179], v[104:107]
	s_waitcnt lgkmcnt(0)
	v_mfma_f32_16x16x32_bf16 v[100:103], v[144:147], v[184:187], v[100:103]
	v_mfma_f32_16x16x32_bf16 v[96:99], v[152:155], v[184:187], v[96:99]
	s_barrier
	ds_read_b128 v[188:191], v137
	ds_read_b128 v[192:195], v137 offset:1024
	ds_read_b128 v[202:205], v137 offset:2048
	ds_read_b128 v[206:209], v137 offset:3072
	s_mov_b32 m0, s66
	s_add_u32 s98, s62, s90
	s_addc_u32 s99, s63, s91
	global_load_lds_dwordx4 v128, s[98:99]
	s_mov_b32 m0, s64
	s_nop 0
	global_load_lds_dwordx4 v130, s[98:99]
	s_barrier
	s_waitcnt lgkmcnt(3)
	v_mfma_f32_16x16x32_bf16 v[92:95], v[188:191], v[156:159], v[92:95]
	s_waitcnt lgkmcnt(1)
	v_mfma_f32_16x16x32_bf16 v[88:91], v[202:205], v[156:159], v[88:91]
	v_mfma_f32_16x16x32_bf16 v[84:87], v[188:191], v[164:167], v[84:87]
	v_mfma_f32_16x16x32_bf16 v[80:83], v[202:205], v[164:167], v[80:83]
	v_mfma_f32_16x16x32_bf16 v[76:79], v[188:191], v[172:175], v[76:79]
	v_mfma_f32_16x16x32_bf16 v[72:75], v[202:205], v[172:175], v[72:75]
	v_mfma_f32_16x16x32_bf16 v[68:71], v[188:191], v[180:183], v[68:71]
	v_mfma_f32_16x16x32_bf16 v[64:67], v[202:205], v[180:183], v[64:67]
	v_mfma_f32_16x16x32_bf16 v[92:95], v[192:195], v[160:163], v[92:95]
	s_waitcnt lgkmcnt(0)
	v_mfma_f32_16x16x32_bf16 v[88:91], v[206:209], v[160:163], v[88:91]
	v_mfma_f32_16x16x32_bf16 v[84:87], v[192:195], v[168:171], v[84:87]
	v_mfma_f32_16x16x32_bf16 v[80:83], v[206:209], v[168:171], v[80:83]
	v_mfma_f32_16x16x32_bf16 v[76:79], v[192:195], v[176:179], v[76:79]
	v_mfma_f32_16x16x32_bf16 v[72:75], v[206:209], v[176:179], v[72:75]
	v_mfma_f32_16x16x32_bf16 v[68:71], v[192:195], v[184:187], v[68:71]
	v_mfma_f32_16x16x32_bf16 v[64:67], v[206:209], v[184:187], v[64:67]
	v_mov_b32_e32 v210, v130
	s_barrier
	ds_read_b128 v[156:159], v136 offset:49152
	ds_read_b128 v[160:163], v136 offset:50176
	ds_read_b128 v[164:167], v135 offset:49152
	ds_read_b128 v[168:171], v135 offset:50176
	ds_read_b128 v[172:175], v134 offset:49152
	ds_read_b128 v[176:179], v134 offset:50176
	ds_read_b128 v[180:183], v133 offset:49152
	ds_read_b128 v[184:187], v133 offset:50176
	v_mov_b32_e32 v211, v197
	s_mov_b32 m0, s65
	s_add_u32 s98, s28, s92
	s_addc_u32 s99, s29, s93
	global_load_lds_dwordx4 v128, s[98:99]
	s_mov_b32 m0, s67
	s_nop 0
	global_load_lds_dwordx4 v130, s[98:99]
	s_barrier
	s_waitcnt lgkmcnt(7)
	v_mfma_f32_16x16x32_bf16 v[60:63], v[140:143], v[156:159], v[60:63]
	v_mfma_f32_16x16x32_bf16 v[56:59], v[148:151], v[156:159], v[56:59]
	s_waitcnt lgkmcnt(5)
	v_mfma_f32_16x16x32_bf16 v[52:55], v[140:143], v[164:167], v[52:55]
	v_mfma_f32_16x16x32_bf16 v[48:51], v[148:151], v[164:167], v[48:51]
	s_waitcnt lgkmcnt(3)
	v_mfma_f32_16x16x32_bf16 v[44:47], v[140:143], v[172:175], v[44:47]
	v_mfma_f32_16x16x32_bf16 v[40:43], v[148:151], v[172:175], v[40:43]
	s_waitcnt lgkmcnt(1)
	v_mfma_f32_16x16x32_bf16 v[36:39], v[140:143], v[180:183], v[36:39]
	v_mfma_f32_16x16x32_bf16 v[32:35], v[148:151], v[180:183], v[32:35]
	v_mfma_f32_16x16x32_bf16 v[60:63], v[144:147], v[160:163], v[60:63]
	v_mfma_f32_16x16x32_bf16 v[56:59], v[152:155], v[160:163], v[56:59]
	v_mfma_f32_16x16x32_bf16 v[52:55], v[144:147], v[168:171], v[52:55]
	v_mfma_f32_16x16x32_bf16 v[48:51], v[152:155], v[168:171], v[48:51]
	v_mfma_f32_16x16x32_bf16 v[44:47], v[144:147], v[176:179], v[44:47]
	v_mfma_f32_16x16x32_bf16 v[40:43], v[152:155], v[176:179], v[40:43]
	s_waitcnt lgkmcnt(0)
	v_mfma_f32_16x16x32_bf16 v[36:39], v[144:147], v[184:187], v[36:39]
	v_mfma_f32_16x16x32_bf16 v[32:35], v[152:155], v[184:187], v[32:35]
	s_barrier
	v_mov_b32_e32 v196, v128
	s_mov_b32 m0, s33
	s_add_u32 s98, s62, s96
	s_addc_u32 s99, s63, s97
	global_load_lds_dwordx4 v128, s[98:99]
	s_mov_b32 m0, s73
	s_nop 0
	global_load_lds_dwordx4 v130, s[98:99]
	s_waitcnt vmcnt(6)
	s_barrier
	v_mfma_f32_16x16x32_bf16 v[28:31], v[188:191], v[156:159], v[28:31]
	v_mfma_f32_16x16x32_bf16 v[24:27], v[202:205], v[156:159], v[24:27]
	v_mfma_f32_16x16x32_bf16 v[20:23], v[188:191], v[164:167], v[20:23]
	v_mfma_f32_16x16x32_bf16 v[16:19], v[202:205], v[164:167], v[16:19]
	v_mfma_f32_16x16x32_bf16 v[12:15], v[188:191], v[172:175], v[12:15]
	v_mfma_f32_16x16x32_bf16 v[8:11], v[202:205], v[172:175], v[8:11]
	v_mfma_f32_16x16x32_bf16 v[4:7], v[188:191], v[180:183], v[4:7]
	v_mfma_f32_16x16x32_bf16 v[0:3], v[202:205], v[180:183], v[0:3]
	v_mfma_f32_16x16x32_bf16 v[28:31], v[192:195], v[160:163], v[28:31]
	v_mfma_f32_16x16x32_bf16 v[24:27], v[206:209], v[160:163], v[24:27]
	v_mfma_f32_16x16x32_bf16 v[20:23], v[192:195], v[168:171], v[20:23]
	v_mfma_f32_16x16x32_bf16 v[16:19], v[206:209], v[168:171], v[16:19]
	v_mfma_f32_16x16x32_bf16 v[12:15], v[192:195], v[176:179], v[12:15]
	v_mfma_f32_16x16x32_bf16 v[8:11], v[206:209], v[176:179], v[8:11]
	v_mfma_f32_16x16x32_bf16 v[4:7], v[192:195], v[184:187], v[4:7]
	v_mfma_f32_16x16x32_bf16 v[0:3], v[206:209], v[184:187], v[0:3]
	s_add_i32 s38, s38, 2
	s_add_u32 s60, s60, 0x100
	s_addc_u32 s61, s61, 0
	s_cmp_lt_u32 s38, 28
	s_barrier
	s_cbranch_scc1 .LBB0_255
	ds_read_b128 v[140:143], v129
	ds_read_b128 v[144:147], v129 offset:1024
	ds_read_b128 v[148:151], v129 offset:2048
	ds_read_b128 v[152:155], v129 offset:3072
	ds_read_b128 v[156:159], v136
	ds_read_b128 v[160:163], v136 offset:1024
	ds_read_b128 v[164:167], v135
	ds_read_b128 v[168:171], v135 offset:1024
	ds_read_b128 v[172:175], v134
	ds_read_b128 v[176:179], v134 offset:1024
	ds_read_b128 v[180:183], v133
	ds_read_b128 v[184:187], v133 offset:1024
	v_mov_b32_e32 v129, v197
	v_lshl_add_u64 v[128:129], s[58:59], 0, v[128:129]
	s_mov_b64 s[28:29], 0xf80
	s_mov_b32 m0, s40
	v_lshl_add_u64 v[128:129], v[128:129], 0, s[28:29]
	v_mov_b32_e32 v131, v197
	global_load_lds_dwordx4 v[128:129], off
	v_lshl_add_u64 v[128:129], s[58:59], 0, v[130:131]
	v_lshl_add_u64 v[128:129], v[128:129], 0, s[28:29]
	s_mov_b32 m0, s39
	s_nop 0
	global_load_lds_dwordx4 v[128:129], off
	s_barrier
	s_waitcnt lgkmcnt(0)
	s_setprio 1
	s_waitcnt lgkmcnt(0)
	v_mfma_f32_16x16x32_bf16 v[124:127], v[140:143], v[156:159], v[124:127]
	v_mfma_f32_16x16x32_bf16 v[120:123], v[148:151], v[156:159], v[120:123]
	v_mfma_f32_16x16x32_bf16 v[116:119], v[140:143], v[164:167], v[116:119]
	v_mfma_f32_16x16x32_bf16 v[112:115], v[148:151], v[164:167], v[112:115]
	v_mfma_f32_16x16x32_bf16 v[108:111], v[140:143], v[172:175], v[108:111]
	v_mfma_f32_16x16x32_bf16 v[100:103], v[140:143], v[180:183], v[100:103]
	v_mfma_f32_16x16x32_bf16 v[96:99], v[148:151], v[180:183], v[96:99]
	v_mfma_f32_16x16x32_bf16 v[124:127], v[144:147], v[160:163], v[124:127]
	v_mfma_f32_16x16x32_bf16 v[120:123], v[152:155], v[160:163], v[120:123]
	v_mfma_f32_16x16x32_bf16 v[116:119], v[144:147], v[168:171], v[116:119]
	v_mfma_f32_16x16x32_bf16 v[112:115], v[152:155], v[168:171], v[112:115]
	v_mfma_f32_16x16x32_bf16 v[108:111], v[144:147], v[176:179], v[108:111]
	v_mfma_f32_16x16x32_bf16 v[104:107], v[148:151], v[172:175], v[104:107]
	v_mfma_f32_16x16x32_bf16 v[100:103], v[144:147], v[184:187], v[100:103]
	v_mfma_f32_16x16x32_bf16 v[96:99], v[152:155], v[184:187], v[96:99]
	v_mfma_f32_16x16x32_bf16 v[128:131], v[152:155], v[176:179], v[104:107]
	s_setprio 0
	s_barrier
	s_nop 2
	ds_read_b128 v[104:107], v139
	ds_read_b128 v[188:191], v139 offset:1024
	ds_read_b128 v[192:195], v139 offset:2048
	ds_read_b128 v[202:205], v139 offset:3072
	s_barrier
	s_waitcnt lgkmcnt(0)
	s_setprio 1
	s_waitcnt lgkmcnt(0)
	v_mfma_f32_16x16x32_bf16 v[92:95], v[104:107], v[156:159], v[92:95]
	v_mfma_f32_16x16x32_bf16 v[84:87], v[104:107], v[164:167], v[84:87]
	v_mfma_f32_16x16x32_bf16 v[76:79], v[104:107], v[172:175], v[76:79]
	v_mfma_f32_16x16x32_bf16 v[68:71], v[104:107], v[180:183], v[68:71]
	v_mfma_f32_16x16x32_bf16 v[64:67], v[192:195], v[180:183], v[64:67]
	v_mfma_f32_16x16x32_bf16 v[92:95], v[188:191], v[160:163], v[92:95]
	v_mfma_f32_16x16x32_bf16 v[88:91], v[192:195], v[156:159], v[88:91]
	v_mfma_f32_16x16x32_bf16 v[84:87], v[188:191], v[168:171], v[84:87]
	v_mfma_f32_16x16x32_bf16 v[80:83], v[192:195], v[164:167], v[80:83]
	v_mfma_f32_16x16x32_bf16 v[76:79], v[188:191], v[176:179], v[76:79]
	v_mfma_f32_16x16x32_bf16 v[72:75], v[192:195], v[172:175], v[72:75]
	v_mfma_f32_16x16x32_bf16 v[68:71], v[188:191], v[184:187], v[68:71]
	v_mfma_f32_16x16x32_bf16 v[64:67], v[202:205], v[184:187], v[64:67]
	v_mfma_f32_16x16x32_bf16 v[156:159], v[202:205], v[160:163], v[88:91]
	v_mfma_f32_16x16x32_bf16 v[160:163], v[202:205], v[168:171], v[80:83]
	v_mfma_f32_16x16x32_bf16 v[164:167], v[202:205], v[176:179], v[72:75]
	s_setprio 0
	s_barrier
	s_nop 0
	ds_read_b128 v[72:75], v136 offset:16384
	ds_read_b128 v[80:83], v136 offset:17408
	ds_read_b128 v[88:91], v135 offset:16384
	ds_read_b128 v[168:171], v135 offset:17408
	ds_read_b128 v[172:175], v134 offset:16384
	ds_read_b128 v[176:179], v134 offset:17408
	ds_read_b128 v[180:183], v133 offset:16384
	ds_read_b128 v[184:187], v133 offset:17408
	s_waitcnt vmcnt(4)
	s_barrier
	s_waitcnt lgkmcnt(0)
	s_setprio 1
	s_waitcnt lgkmcnt(0)
	v_mfma_f32_16x16x32_bf16 v[60:63], v[140:143], v[72:75], v[60:63]
	v_mfma_f32_16x16x32_bf16 v[56:59], v[148:151], v[72:75], v[56:59]
	v_mfma_f32_16x16x32_bf16 v[48:51], v[148:151], v[88:91], v[48:51]
	v_mfma_f32_16x16x32_bf16 v[32:35], v[148:151], v[180:183], v[32:35]
	v_mfma_f32_16x16x32_bf16 v[60:63], v[144:147], v[80:83], v[60:63]
	v_mfma_f32_16x16x32_bf16 v[56:59], v[152:155], v[80:83], v[56:59]
	v_mfma_f32_16x16x32_bf16 v[52:55], v[140:143], v[88:91], v[52:55]
	v_mfma_f32_16x16x32_bf16 v[48:51], v[152:155], v[168:171], v[48:51]
	v_mfma_f32_16x16x32_bf16 v[44:47], v[140:143], v[172:175], v[44:47]
	v_mfma_f32_16x16x32_bf16 v[40:43], v[148:151], v[172:175], v[40:43]
	v_mfma_f32_16x16x32_bf16 v[36:39], v[140:143], v[180:183], v[36:39]
	v_mfma_f32_16x16x32_bf16 v[32:35], v[152:155], v[184:187], v[32:35]
	v_mfma_f32_16x16x32_bf16 v[206:209], v[144:147], v[168:171], v[52:55]
	v_mfma_f32_16x16x32_bf16 v[210:213], v[144:147], v[176:179], v[44:47]
	v_mfma_f32_16x16x32_bf16 v[214:217], v[152:155], v[176:179], v[40:43]
	v_mfma_f32_16x16x32_bf16 v[140:143], v[144:147], v[184:187], v[36:39]
	s_setprio 0
	s_setprio 1
	v_mfma_f32_16x16x32_bf16 v[24:27], v[192:195], v[72:75], v[24:27]
	v_mfma_f32_16x16x32_bf16 v[20:23], v[104:107], v[88:91], v[20:23]
	v_mfma_f32_16x16x32_bf16 v[28:31], v[104:107], v[72:75], v[28:31]
	v_mfma_f32_16x16x32_bf16 v[24:27], v[202:205], v[80:83], v[24:27]
	v_mfma_f32_16x16x32_bf16 v[20:23], v[188:191], v[168:171], v[20:23]
	v_mfma_f32_16x16x32_bf16 v[16:19], v[192:195], v[88:91], v[16:19]
	v_mfma_f32_16x16x32_bf16 v[12:15], v[104:107], v[172:175], v[12:15]
	v_mfma_f32_16x16x32_bf16 v[8:11], v[192:195], v[172:175], v[8:11]
	v_mfma_f32_16x16x32_bf16 v[4:7], v[104:107], v[180:183], v[4:7]
	v_mfma_f32_16x16x32_bf16 v[0:3], v[192:195], v[180:183], v[0:3]
	v_mfma_f32_16x16x32_bf16 v[144:147], v[188:191], v[80:83], v[28:31]
	v_mfma_f32_16x16x32_bf16 v[148:151], v[202:205], v[168:171], v[16:19]
	v_mfma_f32_16x16x32_bf16 v[152:155], v[188:191], v[176:179], v[12:15]
	v_mfma_f32_16x16x32_bf16 v[168:171], v[202:205], v[176:179], v[8:11]
	v_mfma_f32_16x16x32_bf16 v[172:175], v[188:191], v[184:187], v[4:7]
	v_mfma_f32_16x16x32_bf16 v[176:179], v[202:205], v[184:187], v[0:3]
	s_setprio 0
	s_barrier
	ds_read_b128 v[16:19], v138
	ds_read_b128 v[180:183], v138 offset:1024
	ds_read_b128 v[184:187], v138 offset:2048
	ds_read_b128 v[188:191], v138 offset:3072
	ds_read_b128 v[0:3], v136 offset:32768
	ds_read_b128 v[4:7], v136 offset:33792
	ds_read_b128 v[8:11], v135 offset:32768
	ds_read_b128 v[12:15], v135 offset:33792
	ds_read_b128 v[44:47], v134 offset:32768
	ds_read_b128 v[192:195], v134 offset:33792
	ds_read_b128 v[202:205], v133 offset:32768
	ds_read_b128 v[218:221], v133 offset:33792
	s_waitcnt vmcnt(2)
	s_barrier
	s_waitcnt lgkmcnt(0)
	s_setprio 1
	s_waitcnt lgkmcnt(0)
	v_mfma_f32_16x16x32_bf16 v[28:31], v[16:19], v[0:3], v[124:127]
	v_mfma_f32_16x16x32_bf16 v[52:55], v[180:183], v[4:7], v[28:31]
	v_mfma_f32_16x16x32_bf16 v[28:31], v[184:187], v[0:3], v[120:123]
	v_mfma_f32_16x16x32_bf16 v[104:107], v[188:191], v[4:7], v[28:31]
	v_mfma_f32_16x16x32_bf16 v[28:31], v[16:19], v[8:11], v[116:119]
	v_mfma_f32_16x16x32_bf16 v[72:75], v[180:183], v[12:15], v[28:31]
	v_mfma_f32_16x16x32_bf16 v[28:31], v[184:187], v[8:11], v[112:115]
	v_mfma_f32_16x16x32_bf16 v[116:119], v[188:191], v[12:15], v[28:31]
	v_mfma_f32_16x16x32_bf16 v[28:31], v[16:19], v[44:47], v[108:111]
	v_mfma_f32_16x16x32_bf16 v[80:83], v[180:183], v[192:195], v[28:31]
	v_mfma_f32_16x16x32_bf16 v[28:31], v[184:187], v[44:47], v[128:131]
	v_mfma_f32_16x16x32_bf16 v[108:111], v[188:191], v[192:195], v[28:31]
	v_mfma_f32_16x16x32_bf16 v[28:31], v[16:19], v[202:205], v[100:103]
	v_mfma_f32_16x16x32_bf16 v[88:91], v[180:183], v[218:221], v[28:31]
	v_mfma_f32_16x16x32_bf16 v[28:31], v[184:187], v[202:205], v[96:99]
	v_mfma_f32_16x16x32_bf16 v[96:99], v[188:191], v[218:221], v[28:31]
	s_setprio 0
	s_barrier
	ds_read_b128 v[128:131], v137
	ds_read_b128 v[222:225], v137 offset:1024
	ds_read_b128 v[228:231], v137 offset:2048
	ds_read_b128 v[232:235], v137 offset:3072
	s_waitcnt vmcnt(0)
	s_barrier
	s_waitcnt lgkmcnt(0)
	s_setprio 1
	s_waitcnt lgkmcnt(0)
	v_mfma_f32_16x16x32_bf16 v[28:31], v[128:131], v[0:3], v[92:95]
	v_mfma_f32_16x16x32_bf16 v[0:3], v[228:231], v[0:3], v[156:159]
	v_mfma_f32_16x16x32_bf16 v[28:31], v[222:225], v[4:7], v[28:31]
	v_mfma_f32_16x16x32_bf16 v[0:3], v[232:235], v[4:7], v[0:3]
	v_mfma_f32_16x16x32_bf16 v[4:7], v[128:131], v[8:11], v[84:87]
	v_mfma_f32_16x16x32_bf16 v[36:39], v[222:225], v[12:15], v[4:7]
	v_mfma_f32_16x16x32_bf16 v[4:7], v[228:231], v[8:11], v[160:163]
	v_mfma_f32_16x16x32_bf16 v[4:7], v[232:235], v[12:15], v[4:7]
	v_mfma_f32_16x16x32_bf16 v[8:11], v[128:131], v[44:47], v[76:79]
	v_mfma_f32_16x16x32_bf16 v[12:15], v[128:131], v[202:205], v[68:71]
	v_mfma_f32_16x16x32_bf16 v[40:43], v[222:225], v[192:195], v[8:11]
	v_mfma_f32_16x16x32_bf16 v[8:11], v[228:231], v[44:47], v[164:167]
	v_mfma_f32_16x16x32_bf16 v[44:47], v[222:225], v[218:221], v[12:15]
	v_mfma_f32_16x16x32_bf16 v[12:15], v[228:231], v[202:205], v[64:67]
	v_mfma_f32_16x16x32_bf16 v[8:11], v[232:235], v[192:195], v[8:11]
	v_mfma_f32_16x16x32_bf16 v[12:15], v[232:235], v[218:221], v[12:15]
	s_setprio 0
	s_barrier
	ds_read_b128 v[64:67], v136 offset:49152
	ds_read_b128 v[136:139], v136 offset:50176
	ds_read_b128 v[156:159], v135 offset:49152
	ds_read_b128 v[160:163], v135 offset:50176
	ds_read_b128 v[164:167], v134 offset:49152
	ds_read_b128 v[192:195], v134 offset:50176
	ds_read_b128 v[202:205], v133 offset:49152
	ds_read_b128 v[218:221], v133 offset:50176
	s_barrier
	s_waitcnt lgkmcnt(0)
	s_setprio 1
	s_waitcnt lgkmcnt(0)
	v_mfma_f32_16x16x32_bf16 v[56:59], v[184:187], v[64:67], v[56:59]
	v_mfma_f32_16x16x32_bf16 v[48:51], v[184:187], v[156:159], v[48:51]
	v_mfma_f32_16x16x32_bf16 v[60:63], v[16:19], v[64:67], v[60:63]
	v_mfma_f32_16x16x32_bf16 v[92:95], v[188:191], v[136:139], v[56:59]
	v_mfma_f32_16x16x32_bf16 v[56:59], v[16:19], v[156:159], v[206:209]
	v_mfma_f32_16x16x32_bf16 v[84:87], v[188:191], v[160:163], v[48:51]
	v_mfma_f32_16x16x32_bf16 v[48:51], v[16:19], v[164:167], v[210:213]
	v_mfma_f32_16x16x32_bf16 v[16:19], v[16:19], v[202:205], v[140:143]
	v_mfma_f32_16x16x32_bf16 v[120:123], v[180:183], v[192:195], v[48:51]
	v_mfma_f32_16x16x32_bf16 v[48:51], v[184:187], v[164:167], v[214:217]
	v_mfma_f32_16x16x32_bf16 v[124:127], v[180:183], v[218:221], v[16:19]
	v_mfma_f32_16x16x32_bf16 v[16:19], v[184:187], v[202:205], v[32:35]
	v_mfma_f32_16x16x32_bf16 v[100:103], v[180:183], v[136:139], v[60:63]
	v_mfma_f32_16x16x32_bf16 v[112:115], v[180:183], v[160:163], v[56:59]
	v_mfma_f32_16x16x32_bf16 v[76:79], v[188:191], v[192:195], v[48:51]
	v_mfma_f32_16x16x32_bf16 v[68:71], v[188:191], v[218:221], v[16:19]
	s_setprio 0
	s_setprio 1
	v_mfma_f32_16x16x32_bf16 v[16:19], v[128:131], v[64:67], v[144:147]
	v_mfma_f32_16x16x32_bf16 v[48:51], v[222:225], v[136:139], v[16:19]
	v_mfma_f32_16x16x32_bf16 v[16:19], v[228:231], v[64:67], v[24:27]
	v_mfma_f32_16x16x32_bf16 v[20:23], v[128:131], v[156:159], v[20:23]
	v_mfma_f32_16x16x32_bf16 v[24:27], v[128:131], v[164:167], v[152:155]
	v_mfma_f32_16x16x32_bf16 v[32:35], v[128:131], v[202:205], v[172:175]
	v_mfma_f32_16x16x32_bf16 v[56:59], v[222:225], v[160:163], v[20:23]
	v_mfma_f32_16x16x32_bf16 v[20:23], v[228:231], v[156:159], v[148:151]
	v_mfma_f32_16x16x32_bf16 v[60:63], v[222:225], v[192:195], v[24:27]
	v_mfma_f32_16x16x32_bf16 v[24:27], v[228:231], v[164:167], v[168:171]
	v_mfma_f32_16x16x32_bf16 v[64:67], v[222:225], v[218:221], v[32:35]
	v_mfma_f32_16x16x32_bf16 v[32:35], v[228:231], v[202:205], v[176:179]
	v_mfma_f32_16x16x32_bf16 v[16:19], v[232:235], v[136:139], v[16:19]
	v_mfma_f32_16x16x32_bf16 v[20:23], v[232:235], v[160:163], v[20:23]
	v_mfma_f32_16x16x32_bf16 v[24:27], v[232:235], v[192:195], v[24:27]
	v_mfma_f32_16x16x32_bf16 v[32:35], v[232:235], v[218:221], v[32:35]
	s_setprio 0
	s_movk_i32 s9, 0x100
	v_cmp_gt_u32_e32 vcc, s9, v132
	s_barrier
	s_and_saveexec_b64 s[28:29], vcc
	s_cbranch_execz .LBB0_212
	s_barrier
	s_branch .LBB0_212

.LBB0_314:
	ds_read_b128 v[172:175], v170
	ds_read_b128 v[176:179], v170 offset:1024
	ds_read_b128 v[180:183], v170 offset:2048
	ds_read_b128 v[184:187], v170 offset:3072
	s_add_u32 s8, s37, vcc_lo
	s_addc_u32 s9, s38, vcc_hi
	s_add_i32 s40, s34, 0xc000
	s_mov_b32 m0, s40
	s_add_i32 s41, s34, 0xe000
	s_add_u32 s98, s8, s94
	s_addc_u32 s99, s9, s95
	global_load_lds_dwordx4 v160, s[98:99]
	s_mov_b32 m0, s41
	s_nop 0
	global_load_lds_dwordx4 v161, s[98:99]
	ds_read_b128 v[188:191], v166
	ds_read_b128 v[192:195], v166 offset:1024
	ds_read_b128 v[202:205], v165
	ds_read_b128 v[206:209], v165 offset:1024
	ds_read_b128 v[210:213], v163
	ds_read_b128 v[214:217], v163 offset:1024
	ds_read_b128 v[218:221], v162
	ds_read_b128 v[236:239], v162 offset:1024
	s_waitcnt lgkmcnt(8)
	s_barrier
	s_waitcnt lgkmcnt(7)
	v_mfma_f32_16x16x32_bf16 v[44:47], v[172:175], v[188:191], v[44:47]
	v_mfma_f32_16x16x32_bf16 v[40:43], v[180:183], v[188:191], v[40:43]
	s_waitcnt lgkmcnt(5)
	v_mfma_f32_16x16x32_bf16 v[60:63], v[172:175], v[202:205], v[60:63]
	v_mfma_f32_16x16x32_bf16 v[56:59], v[180:183], v[202:205], v[56:59]
	s_waitcnt lgkmcnt(3)
	v_mfma_f32_16x16x32_bf16 v[76:79], v[172:175], v[210:213], v[76:79]
	v_mfma_f32_16x16x32_bf16 v[72:75], v[180:183], v[210:213], v[72:75]
	s_waitcnt lgkmcnt(1)
	v_mfma_f32_16x16x32_bf16 v[92:95], v[172:175], v[218:221], v[92:95]
	v_mfma_f32_16x16x32_bf16 v[88:91], v[180:183], v[218:221], v[88:91]
	v_mfma_f32_16x16x32_bf16 v[44:47], v[176:179], v[192:195], v[44:47]
	v_mfma_f32_16x16x32_bf16 v[40:43], v[184:187], v[192:195], v[40:43]
	v_mfma_f32_16x16x32_bf16 v[60:63], v[176:179], v[206:209], v[60:63]
	v_mfma_f32_16x16x32_bf16 v[56:59], v[184:187], v[206:209], v[56:59]
	v_mfma_f32_16x16x32_bf16 v[76:79], v[176:179], v[214:217], v[76:79]
	v_mfma_f32_16x16x32_bf16 v[72:75], v[184:187], v[214:217], v[72:75]
	s_waitcnt lgkmcnt(0)
	v_mfma_f32_16x16x32_bf16 v[92:95], v[176:179], v[236:239], v[92:95]
	v_mfma_f32_16x16x32_bf16 v[88:91], v[184:187], v[236:239], v[88:91]
	s_barrier
	s_add_i32 s39, s39, 2
	s_add_u32 s28, s6, vcc_lo
	s_addc_u32 s29, s7, vcc_hi
	ds_read_b128 v[240:243], v169
	ds_read_b128 v[244:247], v169 offset:1024
	ds_read_b128 v[248:251], v169 offset:2048
	ds_read_b128 v[228:231], v169 offset:3072
	s_mov_b32 m0, s59
	s_add_u32 s98, s28, s0
	s_addc_u32 s99, s29, s1
	global_load_lds_dwordx4 v160, s[98:99]
	s_mov_b32 m0, s61
	s_nop 0
	global_load_lds_dwordx4 v161, s[98:99]
	s_barrier
	s_waitcnt lgkmcnt(3)
	v_mfma_f32_16x16x32_bf16 v[32:35], v[240:243], v[188:191], v[32:35]
	s_waitcnt lgkmcnt(1)
	v_mfma_f32_16x16x32_bf16 v[36:39], v[248:251], v[188:191], v[36:39]
	v_mfma_f32_16x16x32_bf16 v[48:51], v[240:243], v[202:205], v[48:51]
	v_mfma_f32_16x16x32_bf16 v[52:55], v[248:251], v[202:205], v[52:55]
	v_mfma_f32_16x16x32_bf16 v[64:67], v[240:243], v[210:213], v[64:67]
	v_mfma_f32_16x16x32_bf16 v[68:71], v[248:251], v[210:213], v[68:71]
	v_mfma_f32_16x16x32_bf16 v[80:83], v[240:243], v[218:221], v[80:83]
	v_mfma_f32_16x16x32_bf16 v[84:87], v[248:251], v[218:221], v[84:87]
	v_mfma_f32_16x16x32_bf16 v[32:35], v[244:247], v[192:195], v[32:35]
	s_waitcnt lgkmcnt(0)
	v_mfma_f32_16x16x32_bf16 v[36:39], v[228:231], v[192:195], v[36:39]
	v_mfma_f32_16x16x32_bf16 v[48:51], v[244:247], v[206:209], v[48:51]
	v_mfma_f32_16x16x32_bf16 v[52:55], v[228:231], v[206:209], v[52:55]
	v_mfma_f32_16x16x32_bf16 v[64:67], v[244:247], v[214:217], v[64:67]
	v_mfma_f32_16x16x32_bf16 v[68:71], v[228:231], v[214:217], v[68:71]
	v_mfma_f32_16x16x32_bf16 v[80:83], v[244:247], v[236:239], v[80:83]
	v_mfma_f32_16x16x32_bf16 v[84:87], v[228:231], v[236:239], v[84:87]
	s_add_u32 s92, s90, vcc_lo
	s_addc_u32 s93, s91, vcc_hi
	s_barrier
	ds_read_b128 v[188:191], v166 offset:16384
	ds_read_b128 v[192:195], v166 offset:17408
	ds_read_b128 v[202:205], v165 offset:16384
	ds_read_b128 v[206:209], v165 offset:17408
	ds_read_b128 v[210:213], v163 offset:16384
	ds_read_b128 v[214:217], v163 offset:17408
	ds_read_b128 v[218:221], v162 offset:16384
	ds_read_b128 v[236:239], v162 offset:17408
	s_mov_b32 m0, s34
	s_add_u32 s98, s92, s0
	s_addc_u32 s99, s93, s1
	global_load_lds_dwordx4 v160, s[98:99]
	s_mov_b32 m0, s79
	s_nop 0
	global_load_lds_dwordx4 v161, s[98:99]
	s_barrier
	s_waitcnt lgkmcnt(7)
	v_mfma_f32_16x16x32_bf16 v[108:111], v[172:175], v[188:191], v[108:111]
	v_mfma_f32_16x16x32_bf16 v[104:107], v[180:183], v[188:191], v[104:107]
	s_waitcnt lgkmcnt(5)
	v_mfma_f32_16x16x32_bf16 v[124:127], v[172:175], v[202:205], v[124:127]
	v_mfma_f32_16x16x32_bf16 v[120:123], v[180:183], v[202:205], v[120:123]
	s_waitcnt lgkmcnt(3)
	v_mfma_f32_16x16x32_bf16 v[140:143], v[172:175], v[210:213], v[140:143]
	v_mfma_f32_16x16x32_bf16 v[136:139], v[180:183], v[210:213], v[136:139]
	s_waitcnt lgkmcnt(1)
	v_mfma_f32_16x16x32_bf16 v[156:159], v[172:175], v[218:221], v[156:159]
	v_mfma_f32_16x16x32_bf16 v[152:155], v[180:183], v[218:221], v[152:155]
	v_mfma_f32_16x16x32_bf16 v[108:111], v[176:179], v[192:195], v[108:111]
	v_mfma_f32_16x16x32_bf16 v[104:107], v[184:187], v[192:195], v[104:107]
	v_mfma_f32_16x16x32_bf16 v[124:127], v[176:179], v[206:209], v[124:127]
	v_mfma_f32_16x16x32_bf16 v[120:123], v[184:187], v[206:209], v[120:123]
	v_mfma_f32_16x16x32_bf16 v[140:143], v[176:179], v[214:217], v[140:143]
	v_mfma_f32_16x16x32_bf16 v[136:139], v[184:187], v[214:217], v[136:139]
	s_waitcnt lgkmcnt(0)
	v_mfma_f32_16x16x32_bf16 v[156:159], v[176:179], v[236:239], v[156:159]
	v_mfma_f32_16x16x32_bf16 v[152:155], v[184:187], v[236:239], v[152:155]
	s_barrier
	s_add_u32 s96, s82, vcc_lo
	s_addc_u32 s97, s36, vcc_hi
	s_mov_b32 m0, s52
	s_add_u32 s98, s96, s0
	s_addc_u32 s99, s97, s1
	global_load_lds_dwordx4 v160, s[98:99]
	s_mov_b32 m0, s53
	s_nop 0
	global_load_lds_dwordx4 v161, s[98:99]
	s_waitcnt vmcnt(6)
	s_barrier
	v_mfma_f32_16x16x32_bf16 v[96:99], v[240:243], v[188:191], v[96:99]
	v_mfma_f32_16x16x32_bf16 v[100:103], v[248:251], v[188:191], v[100:103]
	v_mfma_f32_16x16x32_bf16 v[112:115], v[240:243], v[202:205], v[112:115]
	v_mfma_f32_16x16x32_bf16 v[116:119], v[248:251], v[202:205], v[116:119]
	v_mfma_f32_16x16x32_bf16 v[128:131], v[240:243], v[210:213], v[128:131]
	v_mfma_f32_16x16x32_bf16 v[132:135], v[248:251], v[210:213], v[132:135]
	v_mfma_f32_16x16x32_bf16 v[144:147], v[240:243], v[218:221], v[144:147]
	v_mfma_f32_16x16x32_bf16 v[148:151], v[248:251], v[218:221], v[148:151]
	v_mfma_f32_16x16x32_bf16 v[96:99], v[244:247], v[192:195], v[96:99]
	v_mfma_f32_16x16x32_bf16 v[100:103], v[228:231], v[192:195], v[100:103]
	v_mfma_f32_16x16x32_bf16 v[112:115], v[244:247], v[206:209], v[112:115]
	v_mfma_f32_16x16x32_bf16 v[116:119], v[228:231], v[206:209], v[116:119]
	v_mfma_f32_16x16x32_bf16 v[128:131], v[244:247], v[214:217], v[128:131]
	v_mfma_f32_16x16x32_bf16 v[132:135], v[228:231], v[214:217], v[132:135]
	v_mfma_f32_16x16x32_bf16 v[144:147], v[244:247], v[236:239], v[144:147]
	v_mfma_f32_16x16x32_bf16 v[148:151], v[228:231], v[236:239], v[148:151]
	s_barrier
	ds_read_b128 v[172:175], v168
	ds_read_b128 v[176:179], v168 offset:1024
	ds_read_b128 v[180:183], v168 offset:2048
	ds_read_b128 v[184:187], v168 offset:3072
	s_mov_b32 m0, s68
	s_add_u32 s98, s8, s0
	s_addc_u32 s99, s9, s1
	global_load_lds_dwordx4 v160, s[98:99]
	s_mov_b32 m0, s69
	s_nop 0
	global_load_lds_dwordx4 v161, s[98:99]
	ds_read_b128 v[188:191], v166 offset:32768
	ds_read_b128 v[192:195], v166 offset:33792
	ds_read_b128 v[202:205], v165 offset:32768
	ds_read_b128 v[206:209], v165 offset:33792
	ds_read_b128 v[210:213], v163 offset:32768
	ds_read_b128 v[214:217], v163 offset:33792
	ds_read_b128 v[218:221], v162 offset:32768
	ds_read_b128 v[228:231], v162 offset:33792
	s_waitcnt lgkmcnt(8)
	s_barrier
	s_waitcnt lgkmcnt(7)
	v_mfma_f32_16x16x32_bf16 v[44:47], v[172:175], v[188:191], v[44:47]
	v_mfma_f32_16x16x32_bf16 v[40:43], v[180:183], v[188:191], v[40:43]
	s_waitcnt lgkmcnt(5)
	v_mfma_f32_16x16x32_bf16 v[60:63], v[172:175], v[202:205], v[60:63]
	v_mfma_f32_16x16x32_bf16 v[56:59], v[180:183], v[202:205], v[56:59]
	s_waitcnt lgkmcnt(3)
	v_mfma_f32_16x16x32_bf16 v[76:79], v[172:175], v[210:213], v[76:79]
	v_mfma_f32_16x16x32_bf16 v[72:75], v[180:183], v[210:213], v[72:75]
	s_waitcnt lgkmcnt(1)
	v_mfma_f32_16x16x32_bf16 v[92:95], v[172:175], v[218:221], v[92:95]
	v_mfma_f32_16x16x32_bf16 v[88:91], v[180:183], v[218:221], v[88:91]
	v_mfma_f32_16x16x32_bf16 v[44:47], v[176:179], v[192:195], v[44:47]
	v_mfma_f32_16x16x32_bf16 v[40:43], v[184:187], v[192:195], v[40:43]
	v_mfma_f32_16x16x32_bf16 v[60:63], v[176:179], v[206:209], v[60:63]
	v_mfma_f32_16x16x32_bf16 v[56:59], v[184:187], v[206:209], v[56:59]
	v_mfma_f32_16x16x32_bf16 v[76:79], v[176:179], v[214:217], v[76:79]
	v_mfma_f32_16x16x32_bf16 v[72:75], v[184:187], v[214:217], v[72:75]
	s_waitcnt lgkmcnt(0)
	v_mfma_f32_16x16x32_bf16 v[92:95], v[176:179], v[228:231], v[92:95]
	v_mfma_f32_16x16x32_bf16 v[88:91], v[184:187], v[228:231], v[88:91]
	s_barrier
	ds_read_b128 v[236:239], v167
	ds_read_b128 v[240:243], v167 offset:1024
	ds_read_b128 v[244:247], v167 offset:2048
	ds_read_b128 v[248:251], v167 offset:3072
	s_mov_b32 m0, s70
	s_add_u32 s98, s28, s30
	s_addc_u32 s99, s29, s31
	global_load_lds_dwordx4 v160, s[98:99]
	s_mov_b32 m0, s71
	s_nop 0
	global_load_lds_dwordx4 v161, s[98:99]
	s_barrier
	s_waitcnt lgkmcnt(3)
	v_mfma_f32_16x16x32_bf16 v[32:35], v[236:239], v[188:191], v[32:35]
	s_waitcnt lgkmcnt(1)
	v_mfma_f32_16x16x32_bf16 v[36:39], v[244:247], v[188:191], v[36:39]
	v_mfma_f32_16x16x32_bf16 v[48:51], v[236:239], v[202:205], v[48:51]
	v_mfma_f32_16x16x32_bf16 v[52:55], v[244:247], v[202:205], v[52:55]
	v_mfma_f32_16x16x32_bf16 v[64:67], v[236:239], v[210:213], v[64:67]
	v_mfma_f32_16x16x32_bf16 v[68:71], v[244:247], v[210:213], v[68:71]
	v_mfma_f32_16x16x32_bf16 v[80:83], v[236:239], v[218:221], v[80:83]
	v_mfma_f32_16x16x32_bf16 v[84:87], v[244:247], v[218:221], v[84:87]
	v_mfma_f32_16x16x32_bf16 v[32:35], v[240:243], v[192:195], v[32:35]
	s_waitcnt lgkmcnt(0)
	v_mfma_f32_16x16x32_bf16 v[36:39], v[248:251], v[192:195], v[36:39]
	v_mfma_f32_16x16x32_bf16 v[48:51], v[240:243], v[206:209], v[48:51]
	v_mfma_f32_16x16x32_bf16 v[52:55], v[248:251], v[206:209], v[52:55]
	v_mfma_f32_16x16x32_bf16 v[64:67], v[240:243], v[214:217], v[64:67]
	v_mfma_f32_16x16x32_bf16 v[68:71], v[248:251], v[214:217], v[68:71]
	v_mfma_f32_16x16x32_bf16 v[80:83], v[240:243], v[228:231], v[80:83]
	v_mfma_f32_16x16x32_bf16 v[84:87], v[248:251], v[228:231], v[84:87]
	v_mov_b32_e32 v222, v161
	s_barrier
	ds_read_b128 v[188:191], v166 offset:49152
	ds_read_b128 v[192:195], v166 offset:50176
	ds_read_b128 v[202:205], v165 offset:49152
	ds_read_b128 v[206:209], v165 offset:50176
	ds_read_b128 v[210:213], v163 offset:49152
	ds_read_b128 v[214:217], v163 offset:50176
	ds_read_b128 v[218:221], v162 offset:49152
	ds_read_b128 v[228:231], v162 offset:50176
	v_mov_b32_e32 v223, v197
	s_mov_b32 m0, s72
	s_add_u32 s98, s92, s30
	s_addc_u32 s99, s93, s31
	global_load_lds_dwordx4 v160, s[98:99]
	s_mov_b32 m0, s73
	s_nop 0
	global_load_lds_dwordx4 v161, s[98:99]
	s_barrier
	s_waitcnt lgkmcnt(7)
	v_mfma_f32_16x16x32_bf16 v[108:111], v[172:175], v[188:191], v[108:111]
	v_mfma_f32_16x16x32_bf16 v[104:107], v[180:183], v[188:191], v[104:107]
	s_waitcnt lgkmcnt(5)
	v_mfma_f32_16x16x32_bf16 v[124:127], v[172:175], v[202:205], v[124:127]
	v_mfma_f32_16x16x32_bf16 v[120:123], v[180:183], v[202:205], v[120:123]
	s_waitcnt lgkmcnt(3)
	v_mfma_f32_16x16x32_bf16 v[140:143], v[172:175], v[210:213], v[140:143]
	v_mfma_f32_16x16x32_bf16 v[136:139], v[180:183], v[210:213], v[136:139]
	s_waitcnt lgkmcnt(1)
	v_mfma_f32_16x16x32_bf16 v[156:159], v[172:175], v[218:221], v[156:159]
	v_mfma_f32_16x16x32_bf16 v[152:155], v[180:183], v[218:221], v[152:155]
	v_mfma_f32_16x16x32_bf16 v[108:111], v[176:179], v[192:195], v[108:111]
	v_mfma_f32_16x16x32_bf16 v[104:107], v[184:187], v[192:195], v[104:107]
	v_mfma_f32_16x16x32_bf16 v[124:127], v[176:179], v[206:209], v[124:127]
	v_mfma_f32_16x16x32_bf16 v[120:123], v[184:187], v[206:209], v[120:123]
	v_mfma_f32_16x16x32_bf16 v[140:143], v[176:179], v[214:217], v[140:143]
	v_mfma_f32_16x16x32_bf16 v[136:139], v[184:187], v[214:217], v[136:139]
	s_waitcnt lgkmcnt(0)
	v_mfma_f32_16x16x32_bf16 v[156:159], v[176:179], v[228:231], v[156:159]
	v_mfma_f32_16x16x32_bf16 v[152:155], v[184:187], v[228:231], v[152:155]
	s_barrier
	v_mov_b32_e32 v196, v160
	s_mov_b32 m0, s75
	s_add_u32 s98, s96, s30
	s_addc_u32 s99, s97, s31
	global_load_lds_dwordx4 v160, s[98:99]
	s_mov_b32 m0, s89
	s_nop 0
	global_load_lds_dwordx4 v161, s[98:99]
	s_waitcnt vmcnt(6)
	s_barrier
	v_mfma_f32_16x16x32_bf16 v[96:99], v[236:239], v[188:191], v[96:99]
	v_mfma_f32_16x16x32_bf16 v[100:103], v[244:247], v[188:191], v[100:103]
	v_mfma_f32_16x16x32_bf16 v[112:115], v[236:239], v[202:205], v[112:115]
	v_mfma_f32_16x16x32_bf16 v[116:119], v[244:247], v[202:205], v[116:119]
	v_mfma_f32_16x16x32_bf16 v[128:131], v[236:239], v[210:213], v[128:131]
	v_mfma_f32_16x16x32_bf16 v[132:135], v[244:247], v[210:213], v[132:135]
	v_mfma_f32_16x16x32_bf16 v[144:147], v[236:239], v[218:221], v[144:147]
	v_mfma_f32_16x16x32_bf16 v[148:151], v[244:247], v[218:221], v[148:151]
	v_mfma_f32_16x16x32_bf16 v[96:99], v[240:243], v[192:195], v[96:99]
	v_mfma_f32_16x16x32_bf16 v[100:103], v[248:251], v[192:195], v[100:103]
	v_mfma_f32_16x16x32_bf16 v[112:115], v[240:243], v[206:209], v[112:115]
	v_mfma_f32_16x16x32_bf16 v[116:119], v[248:251], v[206:209], v[116:119]
	v_mfma_f32_16x16x32_bf16 v[128:131], v[240:243], v[214:217], v[128:131]
	v_mfma_f32_16x16x32_bf16 v[132:135], v[248:251], v[214:217], v[132:135]
	v_mfma_f32_16x16x32_bf16 v[144:147], v[240:243], v[228:231], v[144:147]
	v_mfma_f32_16x16x32_bf16 v[148:151], v[248:251], v[228:231], v[148:151]
	s_add_u32 vcc_lo, vcc_lo, 0x100
	s_addc_u32 vcc_hi, vcc_hi, 0
	s_cmp_lt_u32 s39, s74
	s_barrier
	s_cbranch_scc1 .LBB0_314
	s_add_i32 s34, s33, -1
	s_lshl_b64 s[6:7], s[34:35], 7
	s_add_u32 s6, s84, s6
	s_addc_u32 s7, s85, s7
	s_mov_b32 m0, s40
	ds_read_b128 v[172:175], v170
	ds_read_b128 v[176:179], v170 offset:1024
	ds_read_b128 v[180:183], v170 offset:2048
	ds_read_b128 v[184:187], v170 offset:3072
	ds_read_b128 v[188:191], v166
	ds_read_b128 v[192:195], v166 offset:1024
	ds_read_b128 v[202:205], v165
	ds_read_b128 v[206:209], v165 offset:1024
	ds_read_b128 v[210:213], v163
	ds_read_b128 v[214:217], v163 offset:1024
	ds_read_b128 v[218:221], v162
	ds_read_b128 v[228:231], v162 offset:1024
	s_nop 0
	global_load_lds_dwordx4 v160, s[6:7]
	s_mov_b32 m0, s41
	s_nop 0
	global_load_lds_dwordx4 v161, s[6:7]
	s_barrier
	s_waitcnt lgkmcnt(0)
	s_setprio 1
	s_waitcnt lgkmcnt(0)
	v_mfma_f32_16x16x32_bf16 v[40:43], v[180:183], v[188:191], v[40:43]
	v_mfma_f32_16x16x32_bf16 v[56:59], v[180:183], v[202:205], v[56:59]
	v_mfma_f32_16x16x32_bf16 v[72:75], v[180:183], v[210:213], v[72:75]
	v_mfma_f32_16x16x32_bf16 v[92:95], v[172:175], v[218:221], v[92:95]
	v_mfma_f32_16x16x32_bf16 v[88:91], v[180:183], v[218:221], v[88:91]
	v_mfma_f32_16x16x32_bf16 v[44:47], v[172:175], v[188:191], v[44:47]
	v_mfma_f32_16x16x32_bf16 v[40:43], v[184:187], v[192:195], v[40:43]
	v_mfma_f32_16x16x32_bf16 v[60:63], v[172:175], v[202:205], v[60:63]
	v_mfma_f32_16x16x32_bf16 v[56:59], v[184:187], v[206:209], v[56:59]
	v_mfma_f32_16x16x32_bf16 v[76:79], v[172:175], v[210:213], v[76:79]
	v_mfma_f32_16x16x32_bf16 v[72:75], v[184:187], v[214:217], v[72:75]
	v_mfma_f32_16x16x32_bf16 v[92:95], v[176:179], v[228:231], v[92:95]
	v_mfma_f32_16x16x32_bf16 v[88:91], v[184:187], v[228:231], v[88:91]
	v_mfma_f32_16x16x32_bf16 v[44:47], v[176:179], v[192:195], v[44:47]
	v_mfma_f32_16x16x32_bf16 v[60:63], v[176:179], v[206:209], v[60:63]
	v_mfma_f32_16x16x32_bf16 v[76:79], v[176:179], v[214:217], v[76:79]
	s_setprio 0
	s_barrier
	ds_read_b128 v[236:239], v169
	ds_read_b128 v[240:243], v169 offset:1024
	ds_read_b128 v[244:247], v169 offset:2048
	ds_read_b128 v[248:251], v169 offset:3072
	s_barrier
	s_waitcnt lgkmcnt(0)
	s_setprio 1
	s_waitcnt lgkmcnt(0)
	v_mfma_f32_16x16x32_bf16 v[36:39], v[244:247], v[188:191], v[36:39]
	v_mfma_f32_16x16x32_bf16 v[32:35], v[236:239], v[188:191], v[32:35]
	v_mfma_f32_16x16x32_bf16 v[188:191], v[248:251], v[192:195], v[36:39]
	v_mfma_f32_16x16x32_bf16 v[36:39], v[236:239], v[202:205], v[48:51]
	v_mfma_f32_16x16x32_bf16 v[48:51], v[240:243], v[206:209], v[36:39]
	v_mfma_f32_16x16x32_bf16 v[36:39], v[244:247], v[202:205], v[52:55]
	v_mfma_f32_16x16x32_bf16 v[32:35], v[240:243], v[192:195], v[32:35]
	v_mfma_f32_16x16x32_bf16 v[192:195], v[248:251], v[206:209], v[36:39]
	v_mfma_f32_16x16x32_bf16 v[36:39], v[236:239], v[210:213], v[64:67]
	v_mfma_f32_16x16x32_bf16 v[64:67], v[240:243], v[214:217], v[36:39]
	v_mfma_f32_16x16x32_bf16 v[36:39], v[244:247], v[210:213], v[68:71]
	v_mfma_f32_16x16x32_bf16 v[202:205], v[248:251], v[214:217], v[36:39]
	v_mfma_f32_16x16x32_bf16 v[36:39], v[236:239], v[218:221], v[80:83]
	v_mfma_f32_16x16x32_bf16 v[80:83], v[240:243], v[228:231], v[36:39]
	v_mfma_f32_16x16x32_bf16 v[36:39], v[244:247], v[218:221], v[84:87]
	v_mfma_f32_16x16x32_bf16 v[206:209], v[248:251], v[228:231], v[36:39]
	s_setprio 0
	s_barrier
	s_nop 4
	ds_read_b128 v[36:39], v166 offset:16384
	ds_read_b128 v[52:55], v166 offset:17408
	ds_read_b128 v[68:71], v165 offset:16384
	ds_read_b128 v[84:87], v165 offset:17408
	ds_read_b128 v[210:213], v163 offset:16384
	ds_read_b128 v[214:217], v163 offset:17408
	ds_read_b128 v[218:221], v162 offset:16384
	ds_read_b128 v[228:231], v162 offset:17408
	s_waitcnt vmcnt(4)
	s_barrier
	s_waitcnt lgkmcnt(0)
	s_setprio 1
	s_waitcnt lgkmcnt(0)
	v_mfma_f32_16x16x32_bf16 v[108:111], v[172:175], v[36:39], v[108:111]
	v_mfma_f32_16x16x32_bf16 v[222:225], v[176:179], v[52:55], v[108:111]
	v_mfma_f32_16x16x32_bf16 v[108:111], v[172:175], v[68:71], v[124:127]
	v_mfma_f32_16x16x32_bf16 v[124:127], v[176:179], v[84:87], v[108:111]
	v_mfma_f32_16x16x32_bf16 v[108:111], v[180:183], v[68:71], v[120:123]
	v_mfma_f32_16x16x32_bf16 v[120:123], v[184:187], v[84:87], v[108:111]
	v_mfma_f32_16x16x32_bf16 v[108:111], v[172:175], v[210:213], v[140:143]
	v_mfma_f32_16x16x32_bf16 v[140:143], v[176:179], v[214:217], v[108:111]
	v_mfma_f32_16x16x32_bf16 v[108:111], v[180:183], v[210:213], v[136:139]
	v_mfma_f32_16x16x32_bf16 v[136:139], v[184:187], v[214:217], v[108:111]
	v_mfma_f32_16x16x32_bf16 v[108:111], v[172:175], v[218:221], v[156:159]
	v_mfma_f32_16x16x32_bf16 v[104:107], v[180:183], v[36:39], v[104:107]
	v_mfma_f32_16x16x32_bf16 v[156:159], v[176:179], v[228:231], v[108:111]
	v_mfma_f32_16x16x32_bf16 v[108:111], v[180:183], v[218:221], v[152:155]
	v_mfma_f32_16x16x32_bf16 v[104:107], v[184:187], v[52:55], v[104:107]
	v_mfma_f32_16x16x32_bf16 v[152:155], v[184:187], v[228:231], v[108:111]
	s_setprio 0
	s_setprio 1
	v_mfma_f32_16x16x32_bf16 v[96:99], v[236:239], v[36:39], v[96:99]
	v_mfma_f32_16x16x32_bf16 v[36:39], v[244:247], v[36:39], v[100:103]
	v_mfma_f32_16x16x32_bf16 v[172:175], v[248:251], v[52:55], v[36:39]
	v_mfma_f32_16x16x32_bf16 v[36:39], v[236:239], v[68:71], v[112:115]
	v_mfma_f32_16x16x32_bf16 v[112:115], v[240:243], v[84:87], v[36:39]
	v_mfma_f32_16x16x32_bf16 v[36:39], v[244:247], v[68:71], v[116:119]
	v_mfma_f32_16x16x32_bf16 v[180:183], v[248:251], v[84:87], v[36:39]
	v_mfma_f32_16x16x32_bf16 v[36:39], v[236:239], v[210:213], v[128:131]
	v_mfma_f32_16x16x32_bf16 v[128:131], v[240:243], v[214:217], v[36:39]
	v_mfma_f32_16x16x32_bf16 v[36:39], v[244:247], v[210:213], v[132:135]
	v_mfma_f32_16x16x32_bf16 v[184:187], v[248:251], v[214:217], v[36:39]
	v_mfma_f32_16x16x32_bf16 v[36:39], v[236:239], v[218:221], v[144:147]
	v_mfma_f32_16x16x32_bf16 v[96:99], v[240:243], v[52:55], v[96:99]
	v_mfma_f32_16x16x32_bf16 v[144:147], v[240:243], v[228:231], v[36:39]
	v_mfma_f32_16x16x32_bf16 v[36:39], v[244:247], v[218:221], v[148:151]
	v_mfma_f32_16x16x32_bf16 v[210:213], v[248:251], v[228:231], v[36:39]
	s_setprio 0
	s_barrier
	ds_read_b128 v[148:151], v168
	ds_read_b128 v[214:217], v168 offset:1024
	ds_read_b128 v[218:221], v168 offset:2048
	ds_read_b128 v[228:231], v168 offset:3072
	ds_read_b128 v[100:103], v166 offset:32768
	ds_read_b128 v[108:111], v166 offset:33792
	ds_read_b128 v[116:119], v165 offset:32768
	ds_read_b128 v[132:135], v165 offset:33792
	ds_read_b128 v[236:239], v163 offset:32768
	ds_read_b128 v[240:243], v163 offset:33792
	ds_read_b128 v[244:247], v162 offset:32768
	ds_read_b128 v[248:251], v162 offset:33792
	s_waitcnt vmcnt(2)
	s_barrier
	s_waitcnt lgkmcnt(0)
	s_setprio 1
	s_waitcnt lgkmcnt(0)
	v_mfma_f32_16x16x32_bf16 v[36:39], v[148:151], v[100:103], v[44:47]
	v_mfma_f32_16x16x32_bf16 v[44:47], v[148:151], v[116:119], v[60:63]
	v_mfma_f32_16x16x32_bf16 v[52:55], v[214:217], v[132:135], v[44:47]
	v_mfma_f32_16x16x32_bf16 v[44:47], v[218:221], v[116:119], v[56:59]
	v_mfma_f32_16x16x32_bf16 v[56:59], v[228:231], v[132:135], v[44:47]
	v_mfma_f32_16x16x32_bf16 v[44:47], v[148:151], v[236:239], v[76:79]
	v_mfma_f32_16x16x32_bf16 v[68:71], v[214:217], v[240:243], v[44:47]
	v_mfma_f32_16x16x32_bf16 v[44:47], v[218:221], v[236:239], v[72:75]
	v_mfma_f32_16x16x32_bf16 v[72:75], v[228:231], v[240:243], v[44:47]
	v_mfma_f32_16x16x32_bf16 v[44:47], v[148:151], v[244:247], v[92:95]
	v_mfma_f32_16x16x32_bf16 v[40:43], v[218:221], v[100:103], v[40:43]
	v_mfma_f32_16x16x32_bf16 v[84:87], v[214:217], v[248:251], v[44:47]
	v_mfma_f32_16x16x32_bf16 v[44:47], v[218:221], v[244:247], v[88:91]
	v_mfma_f32_16x16x32_bf16 v[36:39], v[214:217], v[108:111], v[36:39]
	v_mfma_f32_16x16x32_bf16 v[40:43], v[228:231], v[108:111], v[40:43]
	v_mfma_f32_16x16x32_bf16 v[88:91], v[228:231], v[248:251], v[44:47]
	s_setprio 0
	s_barrier
	s_nop 2
	ds_read_b128 v[44:47], v167
	ds_read_b128 v[60:63], v167 offset:1024
	ds_read_b128 v[76:79], v167 offset:2048
	ds_read_b128 v[232:235], v167 offset:3072
	s_waitcnt vmcnt(0)
	s_barrier
	s_waitcnt lgkmcnt(0)
	s_setprio 1
	s_waitcnt lgkmcnt(0)
	v_mfma_f32_16x16x32_bf16 v[92:95], v[76:79], v[100:103], v[188:191]
	v_mfma_f32_16x16x32_bf16 v[176:179], v[232:235], v[108:111], v[92:95]
	v_mfma_f32_16x16x32_bf16 v[92:95], v[76:79], v[116:119], v[192:195]
	v_mfma_f32_16x16x32_bf16 v[32:35], v[44:47], v[100:103], v[32:35]
	v_mfma_f32_16x16x32_bf16 v[48:51], v[44:47], v[116:119], v[48:51]
	v_mfma_f32_16x16x32_bf16 v[168:171], v[232:235], v[132:135], v[92:95]
	v_mfma_f32_16x16x32_bf16 v[64:67], v[44:47], v[236:239], v[64:67]
	v_mfma_f32_16x16x32_bf16 v[92:95], v[76:79], v[236:239], v[202:205]
	v_mfma_f32_16x16x32_bf16 v[80:83], v[44:47], v[244:247], v[80:83]
	v_mfma_f32_16x16x32_bf16 v[100:103], v[76:79], v[244:247], v[206:209]
	v_mfma_f32_16x16x32_bf16 v[32:35], v[60:63], v[108:111], v[32:35]
	v_mfma_f32_16x16x32_bf16 v[48:51], v[60:63], v[132:135], v[48:51]
	v_mfma_f32_16x16x32_bf16 v[64:67], v[60:63], v[240:243], v[64:67]
	v_mfma_f32_16x16x32_bf16 v[92:95], v[232:235], v[240:243], v[92:95]
	v_mfma_f32_16x16x32_bf16 v[80:83], v[60:63], v[248:251], v[80:83]
	v_mfma_f32_16x16x32_bf16 v[108:111], v[232:235], v[248:251], v[100:103]
	s_setprio 0
	s_barrier
	ds_read_b128 v[188:191], v166 offset:49152
	ds_read_b128 v[192:195], v166 offset:50176
	ds_read_b128 v[202:205], v165 offset:49152
	ds_read_b128 v[206:209], v165 offset:50176
	ds_read_b128 v[236:239], v163 offset:49152
	ds_read_b128 v[240:243], v163 offset:50176
	ds_read_b128 v[244:247], v162 offset:49152
	ds_read_b128 v[160:163], v162 offset:50176
	s_barrier
	s_waitcnt lgkmcnt(0)
	s_setprio 1
	s_waitcnt lgkmcnt(0)
	v_mfma_f32_16x16x32_bf16 v[116:119], v[148:151], v[202:205], v[124:127]
	v_mfma_f32_16x16x32_bf16 v[124:127], v[148:151], v[236:239], v[140:143]
	v_mfma_f32_16x16x32_bf16 v[132:135], v[214:217], v[240:243], v[124:127]
	v_mfma_f32_16x16x32_bf16 v[124:127], v[218:221], v[236:239], v[136:139]
	v_mfma_f32_16x16x32_bf16 v[136:139], v[228:231], v[240:243], v[124:127]
	v_mfma_f32_16x16x32_bf16 v[124:127], v[148:151], v[244:247], v[156:159]
	v_mfma_f32_16x16x32_bf16 v[100:103], v[148:151], v[188:191], v[222:225]
	v_mfma_f32_16x16x32_bf16 v[104:107], v[218:221], v[188:191], v[104:107]
	v_mfma_f32_16x16x32_bf16 v[120:123], v[218:221], v[202:205], v[120:123]
	v_mfma_f32_16x16x32_bf16 v[148:151], v[214:217], v[160:163], v[124:127]
	v_mfma_f32_16x16x32_bf16 v[124:127], v[218:221], v[244:247], v[152:155]
	v_mfma_f32_16x16x32_bf16 v[100:103], v[214:217], v[192:195], v[100:103]
	v_mfma_f32_16x16x32_bf16 v[104:107], v[228:231], v[192:195], v[104:107]
	v_mfma_f32_16x16x32_bf16 v[116:119], v[214:217], v[206:209], v[116:119]
	v_mfma_f32_16x16x32_bf16 v[120:123], v[228:231], v[206:209], v[120:123]
	v_mfma_f32_16x16x32_bf16 v[152:155], v[228:231], v[160:163], v[124:127]
	s_setprio 0
	s_setprio 1
	v_mfma_f32_16x16x32_bf16 v[96:99], v[44:47], v[188:191], v[96:99]
	v_mfma_f32_16x16x32_bf16 v[112:115], v[44:47], v[202:205], v[112:115]
	v_mfma_f32_16x16x32_bf16 v[128:131], v[44:47], v[236:239], v[128:131]
	v_mfma_f32_16x16x32_bf16 v[44:47], v[44:47], v[244:247], v[144:147]
	v_mfma_f32_16x16x32_bf16 v[124:127], v[76:79], v[188:191], v[172:175]
	v_mfma_f32_16x16x32_bf16 v[140:143], v[76:79], v[202:205], v[180:183]
	v_mfma_f32_16x16x32_bf16 v[156:159], v[76:79], v[236:239], v[184:187]
	v_mfma_f32_16x16x32_bf16 v[144:147], v[60:63], v[160:163], v[44:47]
	v_mfma_f32_16x16x32_bf16 v[44:47], v[76:79], v[244:247], v[210:213]
	v_mfma_f32_16x16x32_bf16 v[96:99], v[60:63], v[192:195], v[96:99]
	v_mfma_f32_16x16x32_bf16 v[124:127], v[232:235], v[192:195], v[124:127]
	v_mfma_f32_16x16x32_bf16 v[112:115], v[60:63], v[206:209], v[112:115]
	v_mfma_f32_16x16x32_bf16 v[140:143], v[232:235], v[206:209], v[140:143]
	v_mfma_f32_16x16x32_bf16 v[128:131], v[60:63], v[240:243], v[128:131]
	v_mfma_f32_16x16x32_bf16 v[156:159], v[232:235], v[240:243], v[156:159]
	v_mfma_f32_16x16x32_bf16 v[160:163], v[232:235], v[160:163], v[44:47]
	s_setprio 0
	s_movk_i32 s6, 0x100
	v_cmp_gt_u32_e32 vcc, s6, v164
	s_barrier
	s_and_saveexec_b64 s[6:7], vcc
	s_cbranch_execz .LBB0_317
	s_barrier

.LBB0_568:
	ds_read_b128 v[140:143], v129
	ds_read_b128 v[144:147], v129 offset:1024
	ds_read_b128 v[148:151], v129 offset:2048
	ds_read_b128 v[152:155], v129 offset:3072
	s_add_u32 s28, s8, s10
	s_addc_u32 s29, s9, s11
	s_add_i32 s39, s68, 0xc000
	s_mov_b32 m0, s39
	s_add_i32 s38, s68, 0xe000
	s_add_u32 s98, s28, s44
	s_addc_u32 s99, s29, s45
	global_load_lds_dwordx4 v128, s[98:99]
	s_mov_b32 m0, s38
	s_nop 0
	global_load_lds_dwordx4 v130, s[98:99]
	ds_read_b128 v[156:159], v136
	ds_read_b128 v[160:163], v136 offset:1024
	ds_read_b128 v[164:167], v135
	ds_read_b128 v[168:171], v135 offset:1024
	ds_read_b128 v[172:175], v134
	ds_read_b128 v[176:179], v134 offset:1024
	ds_read_b128 v[180:183], v133
	ds_read_b128 v[184:187], v133 offset:1024
	s_waitcnt lgkmcnt(8)
	s_barrier
	s_waitcnt lgkmcnt(7)
	v_mfma_f32_16x16x32_bf16 v[124:127], v[140:143], v[156:159], v[124:127]
	v_mfma_f32_16x16x32_bf16 v[120:123], v[148:151], v[156:159], v[120:123]
	s_waitcnt lgkmcnt(5)
	v_mfma_f32_16x16x32_bf16 v[116:119], v[140:143], v[164:167], v[116:119]
	v_mfma_f32_16x16x32_bf16 v[112:115], v[148:151], v[164:167], v[112:115]
	s_waitcnt lgkmcnt(3)
	v_mfma_f32_16x16x32_bf16 v[108:111], v[140:143], v[172:175], v[108:111]
	v_mfma_f32_16x16x32_bf16 v[104:107], v[148:151], v[172:175], v[104:107]
	s_waitcnt lgkmcnt(1)
	v_mfma_f32_16x16x32_bf16 v[100:103], v[140:143], v[180:183], v[100:103]
	v_mfma_f32_16x16x32_bf16 v[96:99], v[148:151], v[180:183], v[96:99]
	v_mfma_f32_16x16x32_bf16 v[124:127], v[144:147], v[160:163], v[124:127]
	v_mfma_f32_16x16x32_bf16 v[120:123], v[152:155], v[160:163], v[120:123]
	v_mfma_f32_16x16x32_bf16 v[116:119], v[144:147], v[168:171], v[116:119]
	v_mfma_f32_16x16x32_bf16 v[112:115], v[152:155], v[168:171], v[112:115]
	v_mfma_f32_16x16x32_bf16 v[108:111], v[144:147], v[176:179], v[108:111]
	v_mfma_f32_16x16x32_bf16 v[104:107], v[152:155], v[176:179], v[104:107]
	s_waitcnt lgkmcnt(0)
	v_mfma_f32_16x16x32_bf16 v[100:103], v[144:147], v[184:187], v[100:103]
	v_mfma_f32_16x16x32_bf16 v[96:99], v[152:155], v[184:187], v[96:99]
	s_barrier
	s_add_u32 s56, s6, s10
	s_addc_u32 s57, s7, s11
	ds_read_b128 v[188:191], v139
	ds_read_b128 v[192:195], v139 offset:1024
	ds_read_b128 v[202:205], v139 offset:2048
	ds_read_b128 v[206:209], v139 offset:3072
	s_add_i32 m0, s68, 0x10000
	s_add_u32 s98, s56, s0
	s_addc_u32 s99, s57, s1
	global_load_lds_dwordx4 v128, s[98:99]
	s_add_i32 m0, s68, 0x12000
	s_nop 0
	global_load_lds_dwordx4 v130, s[98:99]
	s_barrier
	s_waitcnt lgkmcnt(3)
	v_mfma_f32_16x16x32_bf16 v[92:95], v[188:191], v[156:159], v[92:95]
	s_waitcnt lgkmcnt(1)
	v_mfma_f32_16x16x32_bf16 v[88:91], v[202:205], v[156:159], v[88:91]
	v_mfma_f32_16x16x32_bf16 v[84:87], v[188:191], v[164:167], v[84:87]
	v_mfma_f32_16x16x32_bf16 v[80:83], v[202:205], v[164:167], v[80:83]
	v_mfma_f32_16x16x32_bf16 v[76:79], v[188:191], v[172:175], v[76:79]
	v_mfma_f32_16x16x32_bf16 v[72:75], v[202:205], v[172:175], v[72:75]
	v_mfma_f32_16x16x32_bf16 v[68:71], v[188:191], v[180:183], v[68:71]
	v_mfma_f32_16x16x32_bf16 v[64:67], v[202:205], v[180:183], v[64:67]
	v_mfma_f32_16x16x32_bf16 v[92:95], v[192:195], v[160:163], v[92:95]
	s_waitcnt lgkmcnt(0)
	v_mfma_f32_16x16x32_bf16 v[88:91], v[206:209], v[160:163], v[88:91]
	v_mfma_f32_16x16x32_bf16 v[84:87], v[192:195], v[168:171], v[84:87]
	v_mfma_f32_16x16x32_bf16 v[80:83], v[206:209], v[168:171], v[80:83]
	v_mfma_f32_16x16x32_bf16 v[76:79], v[192:195], v[176:179], v[76:79]
	v_mfma_f32_16x16x32_bf16 v[72:75], v[206:209], v[176:179], v[72:75]
	v_mfma_f32_16x16x32_bf16 v[68:71], v[192:195], v[184:187], v[68:71]
	v_mfma_f32_16x16x32_bf16 v[64:67], v[206:209], v[184:187], v[64:67]
	s_barrier
	ds_read_b128 v[156:159], v136 offset:16384
	ds_read_b128 v[160:163], v136 offset:17408
	ds_read_b128 v[164:167], v135 offset:16384
	ds_read_b128 v[168:171], v135 offset:17408
	ds_read_b128 v[172:175], v134 offset:16384
	ds_read_b128 v[176:179], v134 offset:17408
	ds_read_b128 v[180:183], v133 offset:16384
	ds_read_b128 v[184:187], v133 offset:17408
	s_mov_b32 m0, s68
	s_add_u32 s98, s28, s0
	s_addc_u32 s99, s29, s1
	global_load_lds_dwordx4 v128, s[98:99]
	s_add_i32 m0, s68, 0x2000
	s_nop 0
	global_load_lds_dwordx4 v130, s[98:99]
	s_barrier
	s_waitcnt lgkmcnt(7)
	v_mfma_f32_16x16x32_bf16 v[60:63], v[140:143], v[156:159], v[60:63]
	v_mfma_f32_16x16x32_bf16 v[56:59], v[148:151], v[156:159], v[56:59]
	s_waitcnt lgkmcnt(5)
	v_mfma_f32_16x16x32_bf16 v[52:55], v[140:143], v[164:167], v[52:55]
	v_mfma_f32_16x16x32_bf16 v[48:51], v[148:151], v[164:167], v[48:51]
	s_waitcnt lgkmcnt(3)
	v_mfma_f32_16x16x32_bf16 v[44:47], v[140:143], v[172:175], v[44:47]
	v_mfma_f32_16x16x32_bf16 v[40:43], v[148:151], v[172:175], v[40:43]
	s_waitcnt lgkmcnt(1)
	v_mfma_f32_16x16x32_bf16 v[36:39], v[140:143], v[180:183], v[36:39]
	v_mfma_f32_16x16x32_bf16 v[32:35], v[148:151], v[180:183], v[32:35]
	v_mfma_f32_16x16x32_bf16 v[60:63], v[144:147], v[160:163], v[60:63]
	v_mfma_f32_16x16x32_bf16 v[56:59], v[152:155], v[160:163], v[56:59]
	v_mfma_f32_16x16x32_bf16 v[52:55], v[144:147], v[168:171], v[52:55]
	v_mfma_f32_16x16x32_bf16 v[48:51], v[152:155], v[168:171], v[48:51]
	v_mfma_f32_16x16x32_bf16 v[44:47], v[144:147], v[176:179], v[44:47]
	v_mfma_f32_16x16x32_bf16 v[40:43], v[152:155], v[176:179], v[40:43]
	s_waitcnt lgkmcnt(0)
	v_mfma_f32_16x16x32_bf16 v[36:39], v[144:147], v[184:187], v[36:39]
	v_mfma_f32_16x16x32_bf16 v[32:35], v[152:155], v[184:187], v[32:35]
	s_barrier
	s_add_i32 m0, s68, 0x14000
	s_add_u32 s98, s56, s46
	s_addc_u32 s99, s57, s47
	global_load_lds_dwordx4 v128, s[98:99]
	s_add_i32 m0, s68, 0x16000
	s_nop 0
	global_load_lds_dwordx4 v130, s[98:99]
	s_waitcnt vmcnt(6)
	s_barrier
	v_mfma_f32_16x16x32_bf16 v[28:31], v[188:191], v[156:159], v[28:31]
	v_mfma_f32_16x16x32_bf16 v[24:27], v[202:205], v[156:159], v[24:27]
	v_mfma_f32_16x16x32_bf16 v[20:23], v[188:191], v[164:167], v[20:23]
	v_mfma_f32_16x16x32_bf16 v[16:19], v[202:205], v[164:167], v[16:19]
	v_mfma_f32_16x16x32_bf16 v[12:15], v[188:191], v[172:175], v[12:15]
	v_mfma_f32_16x16x32_bf16 v[8:11], v[202:205], v[172:175], v[8:11]
	v_mfma_f32_16x16x32_bf16 v[4:7], v[188:191], v[180:183], v[4:7]
	v_mfma_f32_16x16x32_bf16 v[0:3], v[202:205], v[180:183], v[0:3]
	v_mfma_f32_16x16x32_bf16 v[28:31], v[192:195], v[160:163], v[28:31]
	v_mfma_f32_16x16x32_bf16 v[24:27], v[206:209], v[160:163], v[24:27]
	v_mfma_f32_16x16x32_bf16 v[20:23], v[192:195], v[168:171], v[20:23]
	v_mfma_f32_16x16x32_bf16 v[16:19], v[206:209], v[168:171], v[16:19]
	v_mfma_f32_16x16x32_bf16 v[12:15], v[192:195], v[176:179], v[12:15]
	v_mfma_f32_16x16x32_bf16 v[8:11], v[206:209], v[176:179], v[8:11]
	v_mfma_f32_16x16x32_bf16 v[4:7], v[192:195], v[184:187], v[4:7]
	v_mfma_f32_16x16x32_bf16 v[0:3], v[206:209], v[184:187], v[0:3]
	s_barrier
	ds_read_b128 v[140:143], v138
	ds_read_b128 v[144:147], v138 offset:1024
	ds_read_b128 v[148:151], v138 offset:2048
	ds_read_b128 v[152:155], v138 offset:3072
	s_add_i32 m0, s68, 0x4000
	s_add_u32 s98, s28, s46
	s_addc_u32 s99, s29, s47
	global_load_lds_dwordx4 v128, s[98:99]
	s_add_i32 m0, s68, 0x6000
	s_nop 0
	global_load_lds_dwordx4 v130, s[98:99]
	ds_read_b128 v[156:159], v136 offset:32768
	ds_read_b128 v[160:163], v136 offset:33792
	ds_read_b128 v[164:167], v135 offset:32768
	ds_read_b128 v[168:171], v135 offset:33792
	ds_read_b128 v[172:175], v134 offset:32768
	ds_read_b128 v[176:179], v134 offset:33792
	ds_read_b128 v[180:183], v133 offset:32768
	ds_read_b128 v[184:187], v133 offset:33792
	s_waitcnt lgkmcnt(8)
	s_barrier
	s_waitcnt lgkmcnt(7)
	v_mfma_f32_16x16x32_bf16 v[124:127], v[140:143], v[156:159], v[124:127]
	v_mfma_f32_16x16x32_bf16 v[120:123], v[148:151], v[156:159], v[120:123]
	s_waitcnt lgkmcnt(5)
	v_mfma_f32_16x16x32_bf16 v[116:119], v[140:143], v[164:167], v[116:119]
	v_mfma_f32_16x16x32_bf16 v[112:115], v[148:151], v[164:167], v[112:115]
	s_waitcnt lgkmcnt(3)
	v_mfma_f32_16x16x32_bf16 v[108:111], v[140:143], v[172:175], v[108:111]
	v_mfma_f32_16x16x32_bf16 v[104:107], v[148:151], v[172:175], v[104:107]
	s_waitcnt lgkmcnt(1)
	v_mfma_f32_16x16x32_bf16 v[100:103], v[140:143], v[180:183], v[100:103]
	v_mfma_f32_16x16x32_bf16 v[96:99], v[148:151], v[180:183], v[96:99]
	v_mfma_f32_16x16x32_bf16 v[124:127], v[144:147], v[160:163], v[124:127]
	v_mfma_f32_16x16x32_bf16 v[120:123], v[152:155], v[160:163], v[120:123]
	v_mfma_f32_16x16x32_bf16 v[116:119], v[144:147], v[168:171], v[116:119]
	v_mfma_f32_16x16x32_bf16 v[112:115], v[152:155], v[168:171], v[112:115]
	v_mfma_f32_16x16x32_bf16 v[108:111], v[144:147], v[176:179], v[108:111]
	v_mfma_f32_16x16x32_bf16 v[104:107], v[152:155], v[176:179], v[104:107]
	s_waitcnt lgkmcnt(0)
	v_mfma_f32_16x16x32_bf16 v[100:103], v[144:147], v[184:187], v[100:103]
	v_mfma_f32_16x16x32_bf16 v[96:99], v[152:155], v[184:187], v[96:99]
	s_barrier
	ds_read_b128 v[188:191], v137
	ds_read_b128 v[192:195], v137 offset:1024
	ds_read_b128 v[202:205], v137 offset:2048
	ds_read_b128 v[206:209], v137 offset:3072
	s_mov_b32 m0, s69
	s_add_u32 s98, s56, s30
	s_addc_u32 s99, s57, s31
	global_load_lds_dwordx4 v128, s[98:99]
	s_mov_b32 m0, s70
	s_nop 0
	global_load_lds_dwordx4 v130, s[98:99]
	s_barrier
	s_waitcnt lgkmcnt(3)
	v_mfma_f32_16x16x32_bf16 v[92:95], v[188:191], v[156:159], v[92:95]
	s_waitcnt lgkmcnt(1)
	v_mfma_f32_16x16x32_bf16 v[88:91], v[202:205], v[156:159], v[88:91]
	v_mfma_f32_16x16x32_bf16 v[84:87], v[188:191], v[164:167], v[84:87]
	v_mfma_f32_16x16x32_bf16 v[80:83], v[202:205], v[164:167], v[80:83]
	v_mfma_f32_16x16x32_bf16 v[76:79], v[188:191], v[172:175], v[76:79]
	v_mfma_f32_16x16x32_bf16 v[72:75], v[202:205], v[172:175], v[72:75]
	v_mfma_f32_16x16x32_bf16 v[68:71], v[188:191], v[180:183], v[68:71]
	v_mfma_f32_16x16x32_bf16 v[64:67], v[202:205], v[180:183], v[64:67]
	v_mfma_f32_16x16x32_bf16 v[92:95], v[192:195], v[160:163], v[92:95]
	s_waitcnt lgkmcnt(0)
	v_mfma_f32_16x16x32_bf16 v[88:91], v[206:209], v[160:163], v[88:91]
	v_mfma_f32_16x16x32_bf16 v[84:87], v[192:195], v[168:171], v[84:87]
	v_mfma_f32_16x16x32_bf16 v[80:83], v[206:209], v[168:171], v[80:83]
	v_mfma_f32_16x16x32_bf16 v[76:79], v[192:195], v[176:179], v[76:79]
	v_mfma_f32_16x16x32_bf16 v[72:75], v[206:209], v[176:179], v[72:75]
	v_mfma_f32_16x16x32_bf16 v[68:71], v[192:195], v[184:187], v[68:71]
	v_mfma_f32_16x16x32_bf16 v[64:67], v[206:209], v[184:187], v[64:67]
	v_mov_b32_e32 v210, v130
	s_barrier
	ds_read_b128 v[156:159], v136 offset:49152
	ds_read_b128 v[160:163], v136 offset:50176
	ds_read_b128 v[164:167], v135 offset:49152
	ds_read_b128 v[168:171], v135 offset:50176
	ds_read_b128 v[172:175], v134 offset:49152
	ds_read_b128 v[176:179], v134 offset:50176
	ds_read_b128 v[180:183], v133 offset:49152
	ds_read_b128 v[184:187], v133 offset:50176
	v_mov_b32_e32 v211, v197
	s_mov_b32 m0, s71
	s_add_u32 s98, s28, s30
	s_addc_u32 s99, s29, s31
	global_load_lds_dwordx4 v128, s[98:99]
	s_mov_b32 m0, s33
	s_nop 0
	global_load_lds_dwordx4 v130, s[98:99]
	s_barrier
	s_waitcnt lgkmcnt(7)
	v_mfma_f32_16x16x32_bf16 v[60:63], v[140:143], v[156:159], v[60:63]
	v_mfma_f32_16x16x32_bf16 v[56:59], v[148:151], v[156:159], v[56:59]
	s_waitcnt lgkmcnt(5)
	v_mfma_f32_16x16x32_bf16 v[52:55], v[140:143], v[164:167], v[52:55]
	v_mfma_f32_16x16x32_bf16 v[48:51], v[148:151], v[164:167], v[48:51]
	s_waitcnt lgkmcnt(3)
	v_mfma_f32_16x16x32_bf16 v[44:47], v[140:143], v[172:175], v[44:47]
	v_mfma_f32_16x16x32_bf16 v[40:43], v[148:151], v[172:175], v[40:43]
	s_waitcnt lgkmcnt(1)
	v_mfma_f32_16x16x32_bf16 v[36:39], v[140:143], v[180:183], v[36:39]
	v_mfma_f32_16x16x32_bf16 v[32:35], v[148:151], v[180:183], v[32:35]
	v_mfma_f32_16x16x32_bf16 v[60:63], v[144:147], v[160:163], v[60:63]
	v_mfma_f32_16x16x32_bf16 v[56:59], v[152:155], v[160:163], v[56:59]
	v_mfma_f32_16x16x32_bf16 v[52:55], v[144:147], v[168:171], v[52:55]
	v_mfma_f32_16x16x32_bf16 v[48:51], v[152:155], v[168:171], v[48:51]
	v_mfma_f32_16x16x32_bf16 v[44:47], v[144:147], v[176:179], v[44:47]
	v_mfma_f32_16x16x32_bf16 v[40:43], v[152:155], v[176:179], v[40:43]
	s_waitcnt lgkmcnt(0)
	v_mfma_f32_16x16x32_bf16 v[36:39], v[144:147], v[184:187], v[36:39]
	v_mfma_f32_16x16x32_bf16 v[32:35], v[152:155], v[184:187], v[32:35]
	s_barrier
	v_mov_b32_e32 v196, v128
	s_mov_b32 m0, s72
	s_add_u32 s98, s56, s48
	s_addc_u32 s99, s57, s49
	global_load_lds_dwordx4 v128, s[98:99]
	s_mov_b32 m0, s36
	s_nop 0
	global_load_lds_dwordx4 v130, s[98:99]
	s_waitcnt vmcnt(6)
	s_barrier
	v_mfma_f32_16x16x32_bf16 v[28:31], v[188:191], v[156:159], v[28:31]
	v_mfma_f32_16x16x32_bf16 v[24:27], v[202:205], v[156:159], v[24:27]
	v_mfma_f32_16x16x32_bf16 v[20:23], v[188:191], v[164:167], v[20:23]
	v_mfma_f32_16x16x32_bf16 v[16:19], v[202:205], v[164:167], v[16:19]
	v_mfma_f32_16x16x32_bf16 v[12:15], v[188:191], v[172:175], v[12:15]
	v_mfma_f32_16x16x32_bf16 v[8:11], v[202:205], v[172:175], v[8:11]
	v_mfma_f32_16x16x32_bf16 v[4:7], v[188:191], v[180:183], v[4:7]
	v_mfma_f32_16x16x32_bf16 v[0:3], v[202:205], v[180:183], v[0:3]
	v_mfma_f32_16x16x32_bf16 v[28:31], v[192:195], v[160:163], v[28:31]
	v_mfma_f32_16x16x32_bf16 v[24:27], v[206:209], v[160:163], v[24:27]
	v_mfma_f32_16x16x32_bf16 v[20:23], v[192:195], v[168:171], v[20:23]
	v_mfma_f32_16x16x32_bf16 v[16:19], v[206:209], v[168:171], v[16:19]
	v_mfma_f32_16x16x32_bf16 v[12:15], v[192:195], v[176:179], v[12:15]
	v_mfma_f32_16x16x32_bf16 v[8:11], v[206:209], v[176:179], v[8:11]
	v_mfma_f32_16x16x32_bf16 v[4:7], v[192:195], v[184:187], v[4:7]
	v_mfma_f32_16x16x32_bf16 v[0:3], v[206:209], v[184:187], v[0:3]
	s_add_i32 s37, s37, 2
	s_add_u32 s10, s10, 0x100
	s_addc_u32 s11, s11, 0
	s_cmp_lt_u32 s37, 28
	s_barrier
	s_cbranch_scc1 .LBB0_568
	s_lshl_b64 s[4:5], s[4:5], 12
	s_add_u32 s4, s67, s4
	s_addc_u32 s5, s53, s5
	ds_read_b128 v[140:143], v129
	ds_read_b128 v[144:147], v129 offset:1024
	ds_read_b128 v[148:151], v129 offset:2048
	ds_read_b128 v[152:155], v129 offset:3072
	ds_read_b128 v[156:159], v136
	ds_read_b128 v[160:163], v136 offset:1024
	ds_read_b128 v[164:167], v135
	ds_read_b128 v[168:171], v135 offset:1024
	ds_read_b128 v[172:175], v134
	ds_read_b128 v[176:179], v134 offset:1024
	ds_read_b128 v[180:183], v133
	ds_read_b128 v[184:187], v133 offset:1024
	v_mov_b32_e32 v129, v197
	v_lshl_add_u64 v[128:129], s[4:5], 0, v[128:129]
	s_mov_b64 s[6:7], 0xf80
	s_mov_b32 m0, s39
	v_lshl_add_u64 v[128:129], v[128:129], 0, s[6:7]
	v_mov_b32_e32 v131, v197
	global_load_lds_dwordx4 v[128:129], off
	v_lshl_add_u64 v[128:129], s[4:5], 0, v[130:131]
	v_lshl_add_u64 v[128:129], v[128:129], 0, s[6:7]
	s_mov_b32 m0, s38
	s_nop 0
	global_load_lds_dwordx4 v[128:129], off
	s_barrier
	s_waitcnt lgkmcnt(0)
	s_setprio 1
	s_waitcnt lgkmcnt(0)
	v_mfma_f32_16x16x32_bf16 v[124:127], v[140:143], v[156:159], v[124:127]
	v_mfma_f32_16x16x32_bf16 v[120:123], v[148:151], v[156:159], v[120:123]
	v_mfma_f32_16x16x32_bf16 v[116:119], v[140:143], v[164:167], v[116:119]
	v_mfma_f32_16x16x32_bf16 v[112:115], v[148:151], v[164:167], v[112:115]
	v_mfma_f32_16x16x32_bf16 v[100:103], v[140:143], v[180:183], v[100:103]
	v_mfma_f32_16x16x32_bf16 v[96:99], v[148:151], v[180:183], v[96:99]
	v_mfma_f32_16x16x32_bf16 v[124:127], v[144:147], v[160:163], v[124:127]
	v_mfma_f32_16x16x32_bf16 v[120:123], v[152:155], v[160:163], v[120:123]
	v_mfma_f32_16x16x32_bf16 v[116:119], v[144:147], v[168:171], v[116:119]
	v_mfma_f32_16x16x32_bf16 v[112:115], v[152:155], v[168:171], v[112:115]
	v_mfma_f32_16x16x32_bf16 v[108:111], v[140:143], v[172:175], v[108:111]
	v_mfma_f32_16x16x32_bf16 v[104:107], v[148:151], v[172:175], v[104:107]
	v_mfma_f32_16x16x32_bf16 v[100:103], v[144:147], v[184:187], v[100:103]
	v_mfma_f32_16x16x32_bf16 v[96:99], v[152:155], v[184:187], v[96:99]
	v_mfma_f32_16x16x32_bf16 v[128:131], v[144:147], v[176:179], v[108:111]
	v_mfma_f32_16x16x32_bf16 v[188:191], v[152:155], v[176:179], v[104:107]
	s_setprio 0
	s_barrier
	s_nop 1
	ds_read_b128 v[104:107], v139
	ds_read_b128 v[108:111], v139 offset:1024
	ds_read_b128 v[192:195], v139 offset:2048
	ds_read_b128 v[202:205], v139 offset:3072
	s_barrier
	s_waitcnt lgkmcnt(0)
	s_setprio 1
	s_waitcnt lgkmcnt(0)
	v_mfma_f32_16x16x32_bf16 v[84:87], v[104:107], v[164:167], v[84:87]
	v_mfma_f32_16x16x32_bf16 v[80:83], v[192:195], v[164:167], v[80:83]
	v_mfma_f32_16x16x32_bf16 v[68:71], v[104:107], v[180:183], v[68:71]
	v_mfma_f32_16x16x32_bf16 v[64:67], v[192:195], v[180:183], v[64:67]
	v_mfma_f32_16x16x32_bf16 v[92:95], v[104:107], v[156:159], v[92:95]
	v_mfma_f32_16x16x32_bf16 v[88:91], v[192:195], v[156:159], v[88:91]
	v_mfma_f32_16x16x32_bf16 v[84:87], v[108:111], v[168:171], v[84:87]
	v_mfma_f32_16x16x32_bf16 v[80:83], v[202:205], v[168:171], v[80:83]
	v_mfma_f32_16x16x32_bf16 v[76:79], v[104:107], v[172:175], v[76:79]
	v_mfma_f32_16x16x32_bf16 v[72:75], v[192:195], v[172:175], v[72:75]
	v_mfma_f32_16x16x32_bf16 v[68:71], v[108:111], v[184:187], v[68:71]
	v_mfma_f32_16x16x32_bf16 v[64:67], v[202:205], v[184:187], v[64:67]
	v_mfma_f32_16x16x32_bf16 v[206:209], v[108:111], v[160:163], v[92:95]
	v_mfma_f32_16x16x32_bf16 v[156:159], v[202:205], v[160:163], v[88:91]
	v_mfma_f32_16x16x32_bf16 v[160:163], v[108:111], v[176:179], v[76:79]
	v_mfma_f32_16x16x32_bf16 v[164:167], v[202:205], v[176:179], v[72:75]
	s_setprio 0
	s_barrier
	s_nop 0
	ds_read_b128 v[72:75], v136 offset:16384
	ds_read_b128 v[76:79], v136 offset:17408
	ds_read_b128 v[88:91], v135 offset:16384
	ds_read_b128 v[92:95], v135 offset:17408
	ds_read_b128 v[168:171], v134 offset:16384
	ds_read_b128 v[172:175], v134 offset:17408
	ds_read_b128 v[176:179], v133 offset:16384
	ds_read_b128 v[180:183], v133 offset:17408
	s_waitcnt vmcnt(4)
	s_barrier
	s_waitcnt lgkmcnt(0)
	s_setprio 1
	s_waitcnt lgkmcnt(0)
	v_mfma_f32_16x16x32_bf16 v[60:63], v[140:143], v[72:75], v[60:63]
	v_mfma_f32_16x16x32_bf16 v[56:59], v[148:151], v[72:75], v[56:59]
	v_mfma_f32_16x16x32_bf16 v[52:55], v[140:143], v[88:91], v[52:55]
	v_mfma_f32_16x16x32_bf16 v[48:51], v[148:151], v[88:91], v[48:51]
	v_mfma_f32_16x16x32_bf16 v[36:39], v[140:143], v[176:179], v[36:39]
	v_mfma_f32_16x16x32_bf16 v[32:35], v[148:151], v[176:179], v[32:35]
	v_mfma_f32_16x16x32_bf16 v[60:63], v[144:147], v[76:79], v[60:63]
	v_mfma_f32_16x16x32_bf16 v[56:59], v[152:155], v[76:79], v[56:59]
	v_mfma_f32_16x16x32_bf16 v[52:55], v[144:147], v[92:95], v[52:55]
	v_mfma_f32_16x16x32_bf16 v[48:51], v[152:155], v[92:95], v[48:51]
	v_mfma_f32_16x16x32_bf16 v[44:47], v[140:143], v[168:171], v[44:47]
	v_mfma_f32_16x16x32_bf16 v[40:43], v[148:151], v[168:171], v[40:43]
	v_mfma_f32_16x16x32_bf16 v[36:39], v[144:147], v[180:183], v[36:39]
	v_mfma_f32_16x16x32_bf16 v[32:35], v[152:155], v[180:183], v[32:35]
	v_mfma_f32_16x16x32_bf16 v[184:187], v[144:147], v[172:175], v[44:47]
	v_mfma_f32_16x16x32_bf16 v[210:213], v[152:155], v[172:175], v[40:43]
	s_setprio 0
	s_setprio 1
	v_mfma_f32_16x16x32_bf16 v[20:23], v[104:107], v[88:91], v[20:23]
	v_mfma_f32_16x16x32_bf16 v[16:19], v[192:195], v[88:91], v[16:19]
	v_mfma_f32_16x16x32_bf16 v[4:7], v[104:107], v[176:179], v[4:7]
	v_mfma_f32_16x16x32_bf16 v[0:3], v[192:195], v[176:179], v[0:3]
	v_mfma_f32_16x16x32_bf16 v[28:31], v[104:107], v[72:75], v[28:31]
	v_mfma_f32_16x16x32_bf16 v[24:27], v[192:195], v[72:75], v[24:27]
	v_mfma_f32_16x16x32_bf16 v[20:23], v[108:111], v[92:95], v[20:23]
	v_mfma_f32_16x16x32_bf16 v[16:19], v[202:205], v[92:95], v[16:19]
	v_mfma_f32_16x16x32_bf16 v[12:15], v[104:107], v[168:171], v[12:15]
	v_mfma_f32_16x16x32_bf16 v[8:11], v[192:195], v[168:171], v[8:11]
	v_mfma_f32_16x16x32_bf16 v[4:7], v[108:111], v[180:183], v[4:7]
	v_mfma_f32_16x16x32_bf16 v[0:3], v[202:205], v[180:183], v[0:3]
	v_mfma_f32_16x16x32_bf16 v[140:143], v[108:111], v[76:79], v[28:31]
	v_mfma_f32_16x16x32_bf16 v[144:147], v[202:205], v[76:79], v[24:27]
	v_mfma_f32_16x16x32_bf16 v[148:151], v[108:111], v[172:175], v[12:15]
	v_mfma_f32_16x16x32_bf16 v[152:155], v[202:205], v[172:175], v[8:11]
	s_setprio 0
	s_barrier
	s_nop 0
	ds_read_b128 v[8:11], v138
	ds_read_b128 v[12:15], v138 offset:1024
	ds_read_b128 v[168:171], v138 offset:2048
	ds_read_b128 v[172:175], v138 offset:3072
	ds_read_b128 v[24:27], v136 offset:32768
	ds_read_b128 v[28:31], v136 offset:33792
	ds_read_b128 v[40:43], v135 offset:32768
	ds_read_b128 v[44:47], v135 offset:33792
	ds_read_b128 v[176:179], v134 offset:32768
	ds_read_b128 v[180:183], v134 offset:33792
	ds_read_b128 v[192:195], v133 offset:32768
	ds_read_b128 v[202:205], v133 offset:33792
	s_waitcnt vmcnt(2)
	s_barrier
	s_waitcnt lgkmcnt(0)
	s_setprio 1
	s_waitcnt lgkmcnt(0)
	v_mfma_f32_16x16x32_bf16 v[72:75], v[8:11], v[24:27], v[124:127]
	v_mfma_f32_16x16x32_bf16 v[124:127], v[12:15], v[28:31], v[72:75]
	v_mfma_f32_16x16x32_bf16 v[72:75], v[168:171], v[24:27], v[120:123]
	v_mfma_f32_16x16x32_bf16 v[120:123], v[172:175], v[28:31], v[72:75]
	v_mfma_f32_16x16x32_bf16 v[72:75], v[8:11], v[40:43], v[116:119]
	v_mfma_f32_16x16x32_bf16 v[108:111], v[12:15], v[44:47], v[72:75]
	v_mfma_f32_16x16x32_bf16 v[72:75], v[168:171], v[40:43], v[112:115]
	v_mfma_f32_16x16x32_bf16 v[104:107], v[172:175], v[44:47], v[72:75]
	v_mfma_f32_16x16x32_bf16 v[72:75], v[8:11], v[176:179], v[128:131]
	v_mfma_f32_16x16x32_bf16 v[92:95], v[12:15], v[180:183], v[72:75]
	v_mfma_f32_16x16x32_bf16 v[72:75], v[168:171], v[176:179], v[188:191]
	v_mfma_f32_16x16x32_bf16 v[88:91], v[172:175], v[180:183], v[72:75]
	v_mfma_f32_16x16x32_bf16 v[72:75], v[8:11], v[192:195], v[100:103]
	v_mfma_f32_16x16x32_bf16 v[76:79], v[12:15], v[202:205], v[72:75]
	v_mfma_f32_16x16x32_bf16 v[72:75], v[168:171], v[192:195], v[96:99]
	v_mfma_f32_16x16x32_bf16 v[72:75], v[172:175], v[202:205], v[72:75]
	s_setprio 0
	s_barrier
	ds_read_b128 v[128:131], v137
	ds_read_b128 v[188:191], v137 offset:1024
	ds_read_b128 v[214:217], v137 offset:2048
	ds_read_b128 v[218:221], v137 offset:3072
	s_waitcnt vmcnt(0)
	s_barrier
	s_waitcnt lgkmcnt(0)
	s_setprio 1
	s_waitcnt lgkmcnt(0)
	v_mfma_f32_16x16x32_bf16 v[96:99], v[128:131], v[24:27], v[206:209]
	v_mfma_f32_16x16x32_bf16 v[24:27], v[214:217], v[24:27], v[156:159]
	v_mfma_f32_16x16x32_bf16 v[112:115], v[218:221], v[28:31], v[24:27]
	v_mfma_f32_16x16x32_bf16 v[24:27], v[128:131], v[40:43], v[84:87]
	v_mfma_f32_16x16x32_bf16 v[100:103], v[188:191], v[44:47], v[24:27]
	v_mfma_f32_16x16x32_bf16 v[24:27], v[214:217], v[40:43], v[80:83]
	v_mfma_f32_16x16x32_bf16 v[116:119], v[188:191], v[28:31], v[96:99]
	v_mfma_f32_16x16x32_bf16 v[96:99], v[218:221], v[44:47], v[24:27]
	v_mfma_f32_16x16x32_bf16 v[24:27], v[128:131], v[176:179], v[160:163]
	v_mfma_f32_16x16x32_bf16 v[84:87], v[188:191], v[180:183], v[24:27]
	v_mfma_f32_16x16x32_bf16 v[24:27], v[214:217], v[176:179], v[164:167]
	v_mfma_f32_16x16x32_bf16 v[80:83], v[218:221], v[180:183], v[24:27]
	v_mfma_f32_16x16x32_bf16 v[24:27], v[128:131], v[192:195], v[68:71]
	v_mfma_f32_16x16x32_bf16 v[68:71], v[188:191], v[202:205], v[24:27]
	v_mfma_f32_16x16x32_bf16 v[24:27], v[214:217], v[192:195], v[64:67]
	v_mfma_f32_16x16x32_bf16 v[64:67], v[218:221], v[202:205], v[24:27]
	s_setprio 0
	s_barrier
	ds_read_b128 v[156:159], v136 offset:49152
	ds_read_b128 v[136:139], v136 offset:50176
	ds_read_b128 v[160:163], v135 offset:49152
	ds_read_b128 v[164:167], v135 offset:50176
	ds_read_b128 v[176:179], v134 offset:49152
	ds_read_b128 v[180:183], v134 offset:50176
	ds_read_b128 v[192:195], v133 offset:49152
	ds_read_b128 v[202:205], v133 offset:50176
	s_barrier
	s_waitcnt lgkmcnt(0)
	s_setprio 1
	s_waitcnt lgkmcnt(0)
	v_mfma_f32_16x16x32_bf16 v[24:27], v[8:11], v[156:159], v[60:63]
	v_mfma_f32_16x16x32_bf16 v[60:63], v[12:15], v[136:139], v[24:27]
	v_mfma_f32_16x16x32_bf16 v[24:27], v[168:171], v[156:159], v[56:59]
	v_mfma_f32_16x16x32_bf16 v[56:59], v[172:175], v[136:139], v[24:27]
	v_mfma_f32_16x16x32_bf16 v[24:27], v[8:11], v[160:163], v[52:55]
	v_mfma_f32_16x16x32_bf16 v[44:47], v[12:15], v[164:167], v[24:27]
	v_mfma_f32_16x16x32_bf16 v[24:27], v[168:171], v[160:163], v[48:51]
	v_mfma_f32_16x16x32_bf16 v[40:43], v[172:175], v[164:167], v[24:27]
	v_mfma_f32_16x16x32_bf16 v[24:27], v[8:11], v[176:179], v[184:187]
	v_mfma_f32_16x16x32_bf16 v[8:11], v[8:11], v[192:195], v[36:39]
	v_mfma_f32_16x16x32_bf16 v[28:31], v[12:15], v[180:183], v[24:27]
	v_mfma_f32_16x16x32_bf16 v[24:27], v[168:171], v[176:179], v[210:213]
	v_mfma_f32_16x16x32_bf16 v[12:15], v[12:15], v[202:205], v[8:11]
	v_mfma_f32_16x16x32_bf16 v[8:11], v[168:171], v[192:195], v[32:35]
	v_mfma_f32_16x16x32_bf16 v[24:27], v[172:175], v[180:183], v[24:27]
	v_mfma_f32_16x16x32_bf16 v[8:11], v[172:175], v[202:205], v[8:11]
	s_setprio 0
	s_setprio 1
	v_mfma_f32_16x16x32_bf16 v[32:35], v[128:131], v[156:159], v[140:143]
	v_mfma_f32_16x16x32_bf16 v[52:55], v[188:191], v[136:139], v[32:35]
	v_mfma_f32_16x16x32_bf16 v[32:35], v[214:217], v[156:159], v[144:147]
	v_mfma_f32_16x16x32_bf16 v[16:19], v[214:217], v[160:163], v[16:19]
	v_mfma_f32_16x16x32_bf16 v[48:51], v[218:221], v[136:139], v[32:35]
	v_mfma_f32_16x16x32_bf16 v[20:23], v[128:131], v[160:163], v[20:23]
	v_mfma_f32_16x16x32_bf16 v[32:35], v[218:221], v[164:167], v[16:19]
	v_mfma_f32_16x16x32_bf16 v[16:19], v[128:131], v[176:179], v[148:151]
	v_mfma_f32_16x16x32_bf16 v[36:39], v[188:191], v[164:167], v[20:23]
	v_mfma_f32_16x16x32_bf16 v[20:23], v[188:191], v[180:183], v[16:19]
	v_mfma_f32_16x16x32_bf16 v[16:19], v[214:217], v[176:179], v[152:155]
	v_mfma_f32_16x16x32_bf16 v[4:7], v[128:131], v[192:195], v[4:7]
	v_mfma_f32_16x16x32_bf16 v[0:3], v[214:217], v[192:195], v[0:3]
	v_mfma_f32_16x16x32_bf16 v[16:19], v[218:221], v[180:183], v[16:19]
	v_mfma_f32_16x16x32_bf16 v[4:7], v[188:191], v[202:205], v[4:7]
	v_mfma_f32_16x16x32_bf16 v[0:3], v[218:221], v[202:205], v[0:3]
	s_setprio 0
	s_movk_i32 s4, 0x100
	v_cmp_gt_u32_e32 vcc, s4, v132
	s_barrier
	s_and_saveexec_b64 s[4:5], vcc
	s_cbranch_execz .LBB0_571
	s_barrier
